# ballot idiom peephole extended to 31 sites (attn0/attn1/attn2/index), SCC liveness checked across branches
# speedup vs baseline: 1.0083x; 1.0009x over previous
; DI unsigned pk_bf16(float a, float b) { f32x2 v = {a, b}; bf2_t r = __builtin_convertvector(v, bf2_t); return __builtin_bit_cast(unsigned, r); }
; DI float xhalf_max(float v) { const auto r = __builtin_amdgcn_permlane32_swap(__float_as_uint(v), __float_as_uint(v), false, false); return fmaxf(__uint_as_float(r[0]), __uint_as_float(r[1])); }
;     ...
;             float mx = s[0][0];
; #pragma unroll
;             for (int i = 1; i < 16; ++i) mx = fmaxf(mx, s[0][i]);
; #pragma unroll
;             for (int i = 0; i < 16; ++i) mx = fmaxf(mx, s[1][i]);
;             mx = xhalf_max(mx);
;             const float mabs = mi + mx;
;             const bool up = mabs > m + 8.0f;
;             const float mn = up ? __uint_as_float(pk_bf16(mabs, 0.f) << 16) : m;
;             const float shift = mn - mi;
;             if (__ballot(shift != 0.f) != 0) {
;                 if (__ballot(up) != 0) {
;                     const float alpha = __builtin_amdgcn_exp2f(m - mn);
;                     l *= alpha;
; #pragma unroll
;                     for (int db = 0; db < DVB; ++db)
; #pragma unroll
;                         for (int i = 0; i < 16; ++i) o[db][i] *= alpha;
;                     m = mn;
.LBB0_1268:
	s_or_b64 exec, exec, s[8:9]
	v_max_f32_e32 v2, v130, v131
	v_max3_f32 v2, v2, v132, v133
	v_max3_f32 v2, v2, v134, v135
	v_max3_f32 v2, v2, v136, v137
	v_max3_f32 v2, v2, v138, v139
	v_max3_f32 v2, v2, v140, v141
	v_max3_f32 v2, v2, v142, v143
	v_max3_f32 v2, v2, v144, v145
	v_max3_f32 v2, v2, v114, v115
	v_max3_f32 v2, v2, v116, v117
	v_max3_f32 v2, v2, v118, v119
	v_max3_f32 v2, v2, v120, v121
	v_max3_f32 v2, v2, v122, v123
	v_max3_f32 v2, v2, v124, v125
	v_max3_f32 v2, v2, v126, v127
	v_max3_f32 v2, v2, v128, v129
	v_mov_b32_e32 v4, v2
	s_nop 1
	v_permlane32_swap_b32_e32 v2, v4
	v_max_f32_e32 v198, v2, v4
	v_pk_add_f32 v[4:5], v[206:207], v[198:199]
	s_nop 0
	v_cvt_pk_bf16_f32 v2, v4, 0
	v_lshlrev_b32_e32 v2, 16, v2
	v_cmp_gt_f32_e64 s[8:9], v4, v5
	s_nop 1
	v_cndmask_b32_e64 v4, v207, v2, s[8:9]
	v_sub_f32_e32 v2, v4, v206
	v_cmp_neq_f32_e32 vcc, 0, v2
	s_cbranch_vccz .LBB0_1273
	s_and_b64 vcc, s[8:9], exec
	s_cbranch_vccz .LBB0_1271
	v_sub_f32_e32 v5, v207, v4
	v_exp_f32_e32 v8, v5
	s_nop 0
	v_mul_f32_e32 v6, v6, v8
	v_pk_mul_f32 v[112:113], v[112:113], v[8:9] op_sel_hi:[1,0]
	v_pk_mul_f32 v[110:111], v[110:111], v[8:9] op_sel_hi:[1,0]
	v_pk_mul_f32 v[108:109], v[108:109], v[8:9] op_sel_hi:[1,0]
	v_pk_mul_f32 v[106:107], v[106:107], v[8:9] op_sel_hi:[1,0]
	v_pk_mul_f32 v[104:105], v[104:105], v[8:9] op_sel_hi:[1,0]
	v_pk_mul_f32 v[102:103], v[102:103], v[8:9] op_sel_hi:[1,0]
	v_pk_mul_f32 v[100:101], v[100:101], v[8:9] op_sel_hi:[1,0]
	v_pk_mul_f32 v[98:99], v[98:99], v[8:9] op_sel_hi:[1,0]
	v_pk_mul_f32 v[96:97], v[96:97], v[8:9] op_sel_hi:[1,0]
	v_pk_mul_f32 v[94:95], v[94:95], v[8:9] op_sel_hi:[1,0]
	v_pk_mul_f32 v[92:93], v[92:93], v[8:9] op_sel_hi:[1,0]
	v_pk_mul_f32 v[90:91], v[90:91], v[8:9] op_sel_hi:[1,0]
	v_pk_mul_f32 v[88:89], v[88:89], v[8:9] op_sel_hi:[1,0]
	v_pk_mul_f32 v[86:87], v[86:87], v[8:9] op_sel_hi:[1,0]
	v_pk_mul_f32 v[84:85], v[84:85], v[8:9] op_sel_hi:[1,0]
	v_pk_mul_f32 v[82:83], v[82:83], v[8:9] op_sel_hi:[1,0]
	v_pk_mul_f32 v[80:81], v[80:81], v[8:9] op_sel_hi:[1,0]
	v_pk_mul_f32 v[78:79], v[78:79], v[8:9] op_sel_hi:[1,0]
	v_pk_mul_f32 v[76:77], v[76:77], v[8:9] op_sel_hi:[1,0]
	v_pk_mul_f32 v[74:75], v[74:75], v[8:9] op_sel_hi:[1,0]
	v_pk_mul_f32 v[72:73], v[72:73], v[8:9] op_sel_hi:[1,0]
	v_pk_mul_f32 v[70:71], v[70:71], v[8:9] op_sel_hi:[1,0]
	v_pk_mul_f32 v[68:69], v[68:69], v[8:9] op_sel_hi:[1,0]
	v_pk_mul_f32 v[66:67], v[66:67], v[8:9] op_sel_hi:[1,0]
	v_pk_mul_f32 v[64:65], v[64:65], v[8:9] op_sel_hi:[1,0]
	v_pk_mul_f32 v[62:63], v[62:63], v[8:9] op_sel_hi:[1,0]
	v_pk_mul_f32 v[60:61], v[60:61], v[8:9] op_sel_hi:[1,0]
	v_pk_mul_f32 v[58:59], v[58:59], v[8:9] op_sel_hi:[1,0]
	v_pk_mul_f32 v[56:57], v[56:57], v[8:9] op_sel_hi:[1,0]
	v_pk_mul_f32 v[54:55], v[54:55], v[8:9] op_sel_hi:[1,0]
	v_pk_mul_f32 v[52:53], v[52:53], v[8:9] op_sel_hi:[1,0]
	v_pk_mul_f32 v[50:51], v[50:51], v[8:9] op_sel_hi:[1,0]
	s_branch .LBB0_1272

; DI unsigned pk_bf16(float a, float b) { f32x2 v = {a, b}; bf2_t r = __builtin_convertvector(v, bf2_t); return __builtin_bit_cast(unsigned, r); }
; DI float xhalf_max(float v) { const auto r = __builtin_amdgcn_permlane32_swap(__float_as_uint(v), __float_as_uint(v), false, false); return fmaxf(__uint_as_float(r[0]), __uint_as_float(r[1])); }
;     ...
;             float mx = s[0][0];
; #pragma unroll
;             for (int i = 1; i < 16; ++i) mx = fmaxf(mx, s[0][i]);
; #pragma unroll
;             for (int i = 0; i < 16; ++i) mx = fmaxf(mx, s[1][i]);
;             mx = xhalf_max(mx);
;             const float mabs = mi + mx;
;             const bool up = mabs > m + 8.0f;
;             const float mn = up ? __uint_as_float(pk_bf16(mabs, 0.f) << 16) : m;
;             const float shift = mn - mi;
;             if (__ballot(shift != 0.f) != 0) {
;                 if (__ballot(up) != 0) {
;                     const float alpha = __builtin_amdgcn_exp2f(m - mn);
;                     l *= alpha;
; #pragma unroll
;                     for (int db = 0; db < DVB; ++db)
; #pragma unroll
;                         for (int i = 0; i < 16; ++i) o[db][i] *= alpha;
;                     m = mn;
.LBB0_1286:
	s_or_b64 exec, exec, s[52:53]
	v_max_f32_e32 v2, v34, v35
	v_max3_f32 v2, v2, v36, v37
	v_max3_f32 v2, v2, v38, v39
	v_max3_f32 v2, v2, v40, v41
	v_max3_f32 v2, v2, v42, v43
	v_max3_f32 v2, v2, v44, v45
	v_max3_f32 v2, v2, v46, v47
	v_max3_f32 v2, v2, v48, v49
	v_max3_f32 v2, v2, v18, v19
	v_max3_f32 v2, v2, v20, v21
	v_max3_f32 v2, v2, v22, v23
	v_max3_f32 v2, v2, v24, v25
	v_max3_f32 v2, v2, v26, v27
	v_max3_f32 v2, v2, v28, v29
	v_max3_f32 v2, v2, v30, v31
	v_max3_f32 v2, v2, v32, v33
	v_mov_b32_e32 v4, v2
	s_nop 1
	v_permlane32_swap_b32_e32 v2, v4
	v_max_f32_e32 v198, v2, v4
	v_mov_b32_e32 v209, v207
	v_pk_add_f32 v[4:5], v[208:209], v[198:199]
	s_nop 0
	v_cvt_pk_bf16_f32 v2, v4, 0
	v_lshlrev_b32_e32 v2, 16, v2
	v_cmp_gt_f32_e64 s[8:9], v4, v5
	s_nop 1
	v_cndmask_b32_e64 v4, v207, v2, s[8:9]
	v_sub_f32_e32 v2, v4, v208
	v_cmp_neq_f32_e32 vcc, 0, v2
	s_cbranch_vccz .LBB0_1291
	s_and_b64 vcc, s[8:9], exec
	s_cbranch_vccz .LBB0_1289
	v_sub_f32_e32 v5, v207, v4
	v_exp_f32_e32 v8, v5
	s_nop 0
	v_mul_f32_e32 v6, v6, v8
	v_pk_mul_f32 v[112:113], v[112:113], v[8:9] op_sel_hi:[1,0]
	v_pk_mul_f32 v[110:111], v[110:111], v[8:9] op_sel_hi:[1,0]
	v_pk_mul_f32 v[108:109], v[108:109], v[8:9] op_sel_hi:[1,0]
	v_pk_mul_f32 v[106:107], v[106:107], v[8:9] op_sel_hi:[1,0]
	v_pk_mul_f32 v[104:105], v[104:105], v[8:9] op_sel_hi:[1,0]
	v_pk_mul_f32 v[102:103], v[102:103], v[8:9] op_sel_hi:[1,0]
	v_pk_mul_f32 v[100:101], v[100:101], v[8:9] op_sel_hi:[1,0]
	v_pk_mul_f32 v[98:99], v[98:99], v[8:9] op_sel_hi:[1,0]
	v_pk_mul_f32 v[96:97], v[96:97], v[8:9] op_sel_hi:[1,0]
	v_pk_mul_f32 v[94:95], v[94:95], v[8:9] op_sel_hi:[1,0]
	v_pk_mul_f32 v[92:93], v[92:93], v[8:9] op_sel_hi:[1,0]
	v_pk_mul_f32 v[90:91], v[90:91], v[8:9] op_sel_hi:[1,0]
	v_pk_mul_f32 v[88:89], v[88:89], v[8:9] op_sel_hi:[1,0]
	v_pk_mul_f32 v[86:87], v[86:87], v[8:9] op_sel_hi:[1,0]
	v_pk_mul_f32 v[84:85], v[84:85], v[8:9] op_sel_hi:[1,0]
	v_pk_mul_f32 v[82:83], v[82:83], v[8:9] op_sel_hi:[1,0]
	v_pk_mul_f32 v[80:81], v[80:81], v[8:9] op_sel_hi:[1,0]
	v_pk_mul_f32 v[78:79], v[78:79], v[8:9] op_sel_hi:[1,0]
	v_pk_mul_f32 v[76:77], v[76:77], v[8:9] op_sel_hi:[1,0]
	v_pk_mul_f32 v[74:75], v[74:75], v[8:9] op_sel_hi:[1,0]
	v_pk_mul_f32 v[72:73], v[72:73], v[8:9] op_sel_hi:[1,0]
	v_pk_mul_f32 v[70:71], v[70:71], v[8:9] op_sel_hi:[1,0]
	v_pk_mul_f32 v[68:69], v[68:69], v[8:9] op_sel_hi:[1,0]
	v_pk_mul_f32 v[66:67], v[66:67], v[8:9] op_sel_hi:[1,0]
	v_pk_mul_f32 v[64:65], v[64:65], v[8:9] op_sel_hi:[1,0]
	v_pk_mul_f32 v[62:63], v[62:63], v[8:9] op_sel_hi:[1,0]
	v_pk_mul_f32 v[60:61], v[60:61], v[8:9] op_sel_hi:[1,0]
	v_pk_mul_f32 v[58:59], v[58:59], v[8:9] op_sel_hi:[1,0]
	v_pk_mul_f32 v[56:57], v[56:57], v[8:9] op_sel_hi:[1,0]
	v_pk_mul_f32 v[54:55], v[54:55], v[8:9] op_sel_hi:[1,0]
	v_pk_mul_f32 v[52:53], v[52:53], v[8:9] op_sel_hi:[1,0]
	v_pk_mul_f32 v[50:51], v[50:51], v[8:9] op_sel_hi:[1,0]
	s_branch .LBB0_1290

; DI unsigned pk_bf16(float a, float b) { f32x2 v = {a, b}; bf2_t r = __builtin_convertvector(v, bf2_t); return __builtin_bit_cast(unsigned, r); }
; DI float xhalf_max(float v) { const auto r = __builtin_amdgcn_permlane32_swap(__float_as_uint(v), __float_as_uint(v), false, false); return fmaxf(__uint_as_float(r[0]), __uint_as_float(r[1])); }
;     ...
;             float mx = s[0][0];
; #pragma unroll
;             for (int i = 1; i < 16; ++i) mx = fmaxf(mx, s[0][i]);
; #pragma unroll
;             for (int i = 0; i < 16; ++i) mx = fmaxf(mx, s[1][i]);
;             mx = xhalf_max(mx);
;             const float mabs = mi + mx;
;             const bool up = mabs > m + 8.0f;
;             const float mn = up ? __uint_as_float(pk_bf16(mabs, 0.f) << 16) : m;
;             const float shift = mn - mi;
;             if (__ballot(shift != 0.f) != 0) {
;                 if (__ballot(up) != 0) {
;                     const float alpha = __builtin_amdgcn_exp2f(m - mn);
;                     l *= alpha;
; #pragma unroll
;                     for (int db = 0; db < DVB; ++db)
; #pragma unroll
;                         for (int i = 0; i < 16; ++i) o[db][i] *= alpha;
;                     m = mn;
.LBB0_1361:
	s_or_b64 exec, exec, s[8:9]
	v_max_f32_e32 v2, v18, v19
	v_max3_f32 v2, v2, v20, v21
	v_max3_f32 v2, v2, v22, v23
	v_max3_f32 v2, v2, v24, v25
	v_max3_f32 v2, v2, v26, v27
	v_max3_f32 v2, v2, v28, v29
	v_max3_f32 v2, v2, v30, v31
	v_max3_f32 v2, v2, v32, v33
	v_max3_f32 v2, v2, v34, v35
	v_max3_f32 v2, v2, v16, v17
	v_max3_f32 v2, v2, v14, v15
	v_max3_f32 v2, v2, v12, v13
	v_max3_f32 v2, v2, v10, v11
	v_max3_f32 v2, v2, v6, v7
	v_max3_f32 v2, v2, v8, v9
	v_max3_f32 v2, v2, v4, v5
	v_mov_b32_e32 v36, v2
	s_nop 1
	v_permlane32_swap_b32_e32 v2, v36
	v_max_f32_e32 v158, v2, v36
	v_pk_add_f32 v[36:37], v[166:167], v[158:159]
	s_nop 0
	v_cvt_pk_bf16_f32 v2, v36, 0
	v_lshlrev_b32_e32 v2, 16, v2
	v_cmp_gt_f32_e64 s[8:9], v36, v37
	s_nop 1
	v_cndmask_b32_e64 v36, v167, v2, s[8:9]
	v_sub_f32_e32 v2, v36, v166
	v_cmp_neq_f32_e32 vcc, 0, v2
	s_cbranch_vccz .LBB0_1366
	s_and_b64 vcc, s[8:9], exec
	s_cbranch_vccz .LBB0_1364
	v_sub_f32_e32 v37, v167, v36
	v_exp_f32_e32 v38, v37
	s_nop 0
	v_mul_f32_e32 v192, v192, v38
	v_pk_mul_f32 v[96:97], v[96:97], v[38:39] op_sel_hi:[1,0]
	v_pk_mul_f32 v[94:95], v[94:95], v[38:39] op_sel_hi:[1,0]
	v_pk_mul_f32 v[92:93], v[92:93], v[38:39] op_sel_hi:[1,0]
	v_pk_mul_f32 v[90:91], v[90:91], v[38:39] op_sel_hi:[1,0]
	v_pk_mul_f32 v[88:89], v[88:89], v[38:39] op_sel_hi:[1,0]
	v_pk_mul_f32 v[86:87], v[86:87], v[38:39] op_sel_hi:[1,0]
	v_pk_mul_f32 v[84:85], v[84:85], v[38:39] op_sel_hi:[1,0]
	v_pk_mul_f32 v[82:83], v[82:83], v[38:39] op_sel_hi:[1,0]
	v_pk_mul_f32 v[80:81], v[80:81], v[38:39] op_sel_hi:[1,0]
	v_pk_mul_f32 v[78:79], v[78:79], v[38:39] op_sel_hi:[1,0]
	v_pk_mul_f32 v[76:77], v[76:77], v[38:39] op_sel_hi:[1,0]
	v_pk_mul_f32 v[74:75], v[74:75], v[38:39] op_sel_hi:[1,0]
	v_pk_mul_f32 v[72:73], v[72:73], v[38:39] op_sel_hi:[1,0]
	v_pk_mul_f32 v[70:71], v[70:71], v[38:39] op_sel_hi:[1,0]
	v_pk_mul_f32 v[68:69], v[68:69], v[38:39] op_sel_hi:[1,0]
	v_pk_mul_f32 v[66:67], v[66:67], v[38:39] op_sel_hi:[1,0]
	s_branch .LBB0_1365

; DI unsigned pk_bf16(float a, float b) { f32x2 v = {a, b}; bf2_t r = __builtin_convertvector(v, bf2_t); return __builtin_bit_cast(unsigned, r); }
; DI float xhalf_max(float v) { const auto r = __builtin_amdgcn_permlane32_swap(__float_as_uint(v), __float_as_uint(v), false, false); return fmaxf(__uint_as_float(r[0]), __uint_as_float(r[1])); }
;     ...
;             float mx = s[0][0];
; #pragma unroll
;             for (int i = 1; i < 16; ++i) mx = fmaxf(mx, s[0][i]);
; #pragma unroll
;             for (int i = 0; i < 16; ++i) mx = fmaxf(mx, s[1][i]);
;             mx = xhalf_max(mx);
;             const float mabs = mi + mx;
;             const bool up = mabs > m + 8.0f;
;             const float mn = up ? __uint_as_float(pk_bf16(mabs, 0.f) << 16) : m;
;             const float shift = mn - mi;
;             if (__ballot(shift != 0.f) != 0) {
;                 if (__ballot(up) != 0) {
;                     const float alpha = __builtin_amdgcn_exp2f(m - mn);
;                     l *= alpha;
; #pragma unroll
;                     for (int db = 0; db < DVB; ++db)
; #pragma unroll
;                         for (int i = 0; i < 16; ++i) o[db][i] *= alpha;
;                     m = mn;
.LBB0_1382:
	s_or_b64 exec, exec, s[6:7]
	v_max_f32_e32 v2, v50, v51
	v_max3_f32 v2, v2, v52, v53
	v_max3_f32 v2, v2, v54, v55
	v_max3_f32 v2, v2, v56, v57
	v_max3_f32 v2, v2, v58, v59
	v_max3_f32 v2, v2, v60, v61
	v_max3_f32 v2, v2, v62, v63
	v_max3_f32 v2, v2, v64, v65
	v_max3_f32 v2, v2, v98, v99
	v_max3_f32 v2, v2, v16, v17
	v_max3_f32 v2, v2, v14, v15
	v_max3_f32 v2, v2, v12, v13
	v_max3_f32 v2, v2, v10, v11
	v_max3_f32 v2, v2, v8, v9
	v_max3_f32 v2, v2, v6, v7
	v_max3_f32 v2, v2, v4, v5
	v_mov_b32_e32 v100, v2
	s_nop 1
	v_permlane32_swap_b32_e32 v2, v100
	v_max_f32_e32 v158, v2, v100
	v_mov_b32_e32 v169, v167
	v_pk_add_f32 v[100:101], v[168:169], v[158:159]
	s_nop 0
	v_cvt_pk_bf16_f32 v2, v100, 0
	v_lshlrev_b32_e32 v2, 16, v2
	v_cmp_gt_f32_e64 s[6:7], v100, v101
	s_nop 1
	v_cndmask_b32_e64 v100, v167, v2, s[6:7]
	v_sub_f32_e32 v2, v100, v168
	v_cmp_neq_f32_e32 vcc, 0, v2
	s_cbranch_vccz .LBB0_1387
	s_and_b64 vcc, s[6:7], exec
	s_cbranch_vccz .LBB0_1385
	v_sub_f32_e32 v101, v167, v100
	v_exp_f32_e32 v102, v101
	s_nop 0
	v_mul_f32_e32 v192, v192, v102
	v_pk_mul_f32 v[96:97], v[96:97], v[102:103] op_sel_hi:[1,0]
	v_pk_mul_f32 v[94:95], v[94:95], v[102:103] op_sel_hi:[1,0]
	v_pk_mul_f32 v[92:93], v[92:93], v[102:103] op_sel_hi:[1,0]
	v_pk_mul_f32 v[90:91], v[90:91], v[102:103] op_sel_hi:[1,0]
	v_pk_mul_f32 v[88:89], v[88:89], v[102:103] op_sel_hi:[1,0]
	v_pk_mul_f32 v[86:87], v[86:87], v[102:103] op_sel_hi:[1,0]
	v_pk_mul_f32 v[84:85], v[84:85], v[102:103] op_sel_hi:[1,0]
	v_pk_mul_f32 v[82:83], v[82:83], v[102:103] op_sel_hi:[1,0]
	v_pk_mul_f32 v[80:81], v[80:81], v[102:103] op_sel_hi:[1,0]
	v_pk_mul_f32 v[78:79], v[78:79], v[102:103] op_sel_hi:[1,0]
	v_pk_mul_f32 v[76:77], v[76:77], v[102:103] op_sel_hi:[1,0]
	v_pk_mul_f32 v[74:75], v[74:75], v[102:103] op_sel_hi:[1,0]
	v_pk_mul_f32 v[72:73], v[72:73], v[102:103] op_sel_hi:[1,0]
	v_pk_mul_f32 v[70:71], v[70:71], v[102:103] op_sel_hi:[1,0]
	v_pk_mul_f32 v[68:69], v[68:69], v[102:103] op_sel_hi:[1,0]
	v_pk_mul_f32 v[66:67], v[66:67], v[102:103] op_sel_hi:[1,0]
	s_branch .LBB0_1386

; DI void hist_select(const unsigned* hrow, int need, int lane, int& bsel, int& above, bool& hit) {
;     const u32x4 w0 = *(const u32x4*)(hrow + 8 * lane), w1 = *(const u32x4*)(hrow + 8 * lane + 4);
;     unsigned wv[8] = {w0.x, w0.y, w0.z, w0.w, w1.x, w1.y, w1.z, w1.w};
;     int cnt[16]; int tot = 0;
; #pragma unroll
;     for (int j = 0; j < 8; ++j) { cnt[2 * j] = (int)(wv[j] & 0xffffu); cnt[2 * j + 1] = (int)(wv[j] >> 16); tot += cnt[2 * j] + cnt[2 * j + 1]; }
;     int inc = tot;
; #pragma unroll
;     for (int d = 1; d < 64; d <<= 1) { const int o = __shfl_down(inc, d); if (lane + d < 64) inc += o; }
;     const int exc = inc - tot;
;     const bool pred = (inc >= need) && (exc < need);
;     const u64 bal = __ballot(pred);
;     int mybin = 0, myabove = exc; bool found = false; int run = exc;
; #pragma unroll
;     for (int j = 15; j >= 0; --j) { if (!found && run + cnt[j] >= need) { found = true; mybin = 16 * lane + j; myabove = run; } run += cnt[j]; }
;     hit = (bal != 0);
;     if (bal == 0) {
;         const int total = __shfl(inc, 0), c0 = __shfl(cnt[0], 0);
;         bsel = 0; above = total - c0;
;     } else {
;         const int L = __ffsll((long long)bal) - 1;
;         bsel = __shfl(mybin, L); above = __shfl(myabove, L);
;     }
.LBB0_2589:
	v_add_u32_e32 v110, v121, v120
	ds_read_b128 v[2:5], v110
	ds_read_b128 v[16:19], v110 offset:16
	v_lshlrev_b32_e32 v109, 2, v160
	v_or_b32_e32 v83, 0x80, v109
	s_waitcnt lgkmcnt(1)
	v_add_u32_sdwa v1, v2, v2 dst_sel:DWORD dst_unused:UNUSED_PAD src0_sel:WORD_1 src1_sel:WORD_0
	v_and_b32_e32 v6, 0xffff, v3
	v_lshrrev_b32_e32 v3, 16, v3
	v_and_b32_e32 v7, 0xffff, v4
	v_add3_u32 v1, v1, v3, v6
	v_lshrrev_b32_e32 v8, 16, v4
	v_add3_u32 v1, v1, v8, v7
	v_and_b32_e32 v9, 0xffff, v5
	v_lshrrev_b32_e32 v10, 16, v5
	v_add3_u32 v1, v1, v10, v9
	s_waitcnt lgkmcnt(0)
	v_and_b32_e32 v11, 0xffff, v16
	v_lshrrev_b32_e32 v12, 16, v16
	v_add3_u32 v1, v1, v12, v11
	v_and_b32_e32 v13, 0xffff, v17
	v_lshrrev_b32_e32 v14, 16, v17
	v_add3_u32 v1, v1, v14, v13
	v_and_b32_e32 v15, 0xffff, v18
	v_lshrrev_b32_e32 v16, 16, v18
	v_and_b32_e32 v4, 63, v160
	v_add3_u32 v1, v1, v16, v15
	v_and_b32_e32 v17, 0xffff, v19
	v_lshrrev_b32_e32 v18, 16, v19
	v_cmp_ne_u32_e32 vcc, 63, v4
	v_add3_u32 v19, v1, v18, v17
	s_nop 0
	v_addc_co_u32_e32 v1, vcc, 0, v160, vcc
	v_lshlrev_b32_e32 v1, 2, v1
	ds_bpermute_b32 v5, v1, v19
	v_cmp_gt_u32_e32 vcc, 62, v4
	s_waitcnt lgkmcnt(0)
	v_cndmask_b32_e64 v5, v5, 0, s[6:7]
	v_cndmask_b32_e64 v20, 0, 2, vcc
	v_add_lshl_u32 v104, v20, v160, 2
	v_add_u32_e32 v5, v19, v5
	ds_bpermute_b32 v20, v104, v5
	v_cmp_gt_u32_e32 vcc, 60, v4
	s_waitcnt lgkmcnt(0)
	v_cndmask_b32_e64 v20, 0, v20, s[8:9]
	v_cndmask_b32_e64 v21, 0, 4, vcc
	v_add_lshl_u32 v105, v21, v160, 2
	v_add_u32_e32 v5, v5, v20
	ds_bpermute_b32 v20, v105, v5
	v_cmp_gt_u32_e32 vcc, 56, v4
	s_waitcnt lgkmcnt(0)
	v_cndmask_b32_e64 v20, 0, v20, s[10:11]
	v_cndmask_b32_e64 v21, 0, 8, vcc
	v_add_lshl_u32 v106, v21, v160, 2
	v_add_u32_e32 v5, v5, v20
	ds_bpermute_b32 v20, v106, v5
	v_cmp_gt_u32_e32 vcc, 48, v4
	s_nop 1
	v_cndmask_b32_e64 v4, 0, 16, vcc
	v_add_lshl_u32 v108, v4, v160, 2
	s_waitcnt lgkmcnt(0)
	v_cndmask_b32_e64 v4, 0, v20, s[12:13]
	v_add_u32_e32 v4, v5, v4
	ds_bpermute_b32 v5, v108, v4
	s_waitcnt lgkmcnt(0)
	v_cndmask_b32_e64 v5, 0, v5, s[14:15]
	v_add_u32_e32 v4, v4, v5
	ds_bpermute_b32 v5, v83, v4
	s_waitcnt lgkmcnt(0)
	v_cndmask_b32_e64 v5, 0, v5, s[16:17]
	v_add_u32_e32 v5, v4, v5
	v_sub_u32_e32 v4, v5, v19
	v_cmp_lt_i32_e32 vcc, 31, v5
	v_cmp_gt_i32_e64 s[26:27], 32, v4
	s_and_b64 vcc, vcc, s[26:27]
	s_and_b64 s[26:27], vcc, exec
	s_cbranch_vccz .LBB0_2591
	v_add_u32_e32 v4, v4, v18
	v_add_u32_e32 v5, v4, v17
	v_cmp_lt_i32_e32 vcc, 31, v5
	v_add_u32_e32 v20, v5, v16
	v_cmp_lt_i32_e64 s[28:29], 31, v4
	v_cndmask_b32_e32 v5, 0, v125, vcc
	v_cmp_lt_i32_e64 s[30:31], 31, v20
	v_cndmask_b32_e64 v4, v5, v124, s[28:29]
	v_add_u32_e32 v21, v20, v15
	v_cndmask_b32_e64 v5, v4, v126, s[30:31]
	s_or_b64 vcc, s[28:29], vcc
	v_cndmask_b32_e32 v4, v5, v4, vcc
	v_cmp_lt_i32_e64 s[28:29], 31, v21
	v_add_u32_e32 v22, v21, v14
	s_or_b64 vcc, vcc, s[30:31]
	v_cndmask_b32_e64 v5, v4, v127, s[28:29]
	v_cndmask_b32_e32 v4, v5, v4, vcc
	v_cmp_lt_i32_e64 s[30:31], 31, v22
	v_add_u32_e32 v23, v22, v13
	s_or_b64 vcc, vcc, s[28:29]
	v_cndmask_b32_e64 v5, v4, v128, s[30:31]
	v_cndmask_b32_e32 v4, v5, v4, vcc
	v_cmp_lt_i32_e64 s[28:29], 31, v23
	v_add_u32_e32 v24, v23, v12
	s_or_b64 vcc, vcc, s[30:31]
	v_cndmask_b32_e64 v5, v4, v129, s[28:29]
	v_cndmask_b32_e32 v4, v5, v4, vcc
	v_cmp_lt_i32_e64 s[30:31], 31, v24
	v_add_u32_e32 v25, v24, v11
	s_or_b64 vcc, vcc, s[28:29]
	v_cndmask_b32_e64 v5, v4, v130, s[30:31]
	v_cndmask_b32_e32 v4, v5, v4, vcc
	v_cmp_lt_i32_e64 s[28:29], 31, v25
	v_add_u32_e32 v26, v25, v10
	s_or_b64 vcc, vcc, s[30:31]
	v_cndmask_b32_e64 v5, v4, v131, s[28:29]
	v_cndmask_b32_e32 v4, v5, v4, vcc
	v_cmp_lt_i32_e64 s[30:31], 31, v26
	v_add_u32_e32 v27, v26, v9
	s_or_b64 vcc, vcc, s[28:29]
	v_cndmask_b32_e64 v5, v4, v132, s[30:31]
	v_cndmask_b32_e32 v4, v5, v4, vcc
	v_cmp_lt_i32_e64 s[28:29], 31, v27
	v_add_u32_e32 v28, v27, v8
	s_or_b64 vcc, vcc, s[30:31]
	v_cndmask_b32_e64 v5, v4, v133, s[28:29]
	v_cndmask_b32_e32 v4, v5, v4, vcc
	v_cmp_lt_i32_e64 s[30:31], 31, v28
	v_add_u32_e32 v29, v28, v7
	s_or_b64 vcc, vcc, s[28:29]
	v_cndmask_b32_e64 v5, v4, v134, s[30:31]
	v_cndmask_b32_e32 v4, v5, v4, vcc
	v_cmp_lt_i32_e64 s[28:29], 31, v29
	v_add_u32_e32 v30, v29, v3
	s_or_b64 vcc, vcc, s[30:31]
	v_cndmask_b32_e64 v5, v4, v135, s[28:29]
	v_cndmask_b32_e32 v4, v5, v4, vcc
	v_cmp_lt_i32_e64 s[30:31], 31, v30
	v_add_u32_e32 v31, v30, v6
	s_or_b64 vcc, vcc, s[28:29]
	v_cndmask_b32_e64 v5, v4, v136, s[30:31]
	v_add_u32_sdwa v32, v31, v2 dst_sel:DWORD dst_unused:UNUSED_PAD src0_sel:DWORD src1_sel:WORD_1
	v_cndmask_b32_e32 v4, v5, v4, vcc
	v_cmp_lt_i32_e64 s[28:29], 31, v31
	s_or_b64 vcc, vcc, s[30:31]
	v_add_u32_sdwa v20, v32, v2 dst_sel:DWORD dst_unused:UNUSED_PAD src0_sel:DWORD src1_sel:WORD_0
	v_cndmask_b32_e64 v5, v4, v137, s[28:29]
	v_cndmask_b32_e32 v5, v5, v4, vcc
	v_cmp_gt_i32_e64 s[30:31], 32, v20
	s_ff1_i32_b64 s0, s[26:27]
	s_nop 0
	v_cndmask_b32_e64 v5, v120, v5, s[30:31]
	v_cmp_lt_i32_e64 s[30:31], 31, v32
	s_nop 1
	v_cndmask_b32_e64 v5, v5, v138, s[30:31]
	v_cndmask_b32_e64 v5, v5, v137, s[28:29]
	v_cndmask_b32_e32 v4, v5, v4, vcc
	v_and_or_b32 v5, v160, 64, s0
	v_lshlrev_b32_e32 v5, 2, v5
	ds_bpermute_b32 v5, v5, v4
	s_branch .LBB0_2592

; DI void hist_select(const unsigned* hrow, int need, int lane, int& bsel, int& above, bool& hit) {
;     const u32x4 w0 = *(const u32x4*)(hrow + 8 * lane), w1 = *(const u32x4*)(hrow + 8 * lane + 4);
;     unsigned wv[8] = {w0.x, w0.y, w0.z, w0.w, w1.x, w1.y, w1.z, w1.w};
;     int cnt[16]; int tot = 0;
; #pragma unroll
;     for (int j = 0; j < 8; ++j) { cnt[2 * j] = (int)(wv[j] & 0xffffu); cnt[2 * j + 1] = (int)(wv[j] >> 16); tot += cnt[2 * j] + cnt[2 * j + 1]; }
;     int inc = tot;
; #pragma unroll
;     for (int d = 1; d < 64; d <<= 1) { const int o = __shfl_down(inc, d); if (lane + d < 64) inc += o; }
;     const int exc = inc - tot;
;     const bool pred = (inc >= need) && (exc < need);
;     const u64 bal = __ballot(pred);
;     int mybin = 0, myabove = exc; bool found = false; int run = exc;
; #pragma unroll
;     for (int j = 15; j >= 0; --j) { if (!found && run + cnt[j] >= need) { found = true; mybin = 16 * lane + j; myabove = run; } run += cnt[j]; }
;     hit = (bal != 0);
;     if (bal == 0) {
;         const int total = __shfl(inc, 0), c0 = __shfl(cnt[0], 0);
;         bsel = 0; above = total - c0;
;     } else {
;         const int L = __ffsll((long long)bal) - 1;
;         bsel = __shfl(mybin, L); above = __shfl(myabove, L);
;     }
.LBB0_2592:
	ds_bpermute_b32 v4, v1, v19
	s_waitcnt lgkmcnt(0)
	v_cndmask_b32_e64 v4, v4, 0, s[6:7]
	v_add_u32_e32 v4, v4, v19
	ds_bpermute_b32 v20, v104, v4
	s_waitcnt lgkmcnt(0)
	v_cndmask_b32_e64 v20, 0, v20, s[8:9]
	v_add_u32_e32 v4, v20, v4
	ds_bpermute_b32 v20, v105, v4
	s_waitcnt lgkmcnt(0)
	v_cndmask_b32_e64 v20, 0, v20, s[10:11]
	v_add_u32_e32 v4, v20, v4
	ds_bpermute_b32 v20, v106, v4
	s_waitcnt lgkmcnt(0)
	v_cndmask_b32_e64 v20, 0, v20, s[12:13]
	v_add_u32_e32 v4, v20, v4
	ds_bpermute_b32 v20, v108, v4
	s_waitcnt lgkmcnt(0)
	v_cndmask_b32_e64 v20, 0, v20, s[14:15]
	v_add_u32_e32 v20, v20, v4
	ds_bpermute_b32 v21, v83, v20
	v_mov_b32_e32 v4, 0
	s_waitcnt lgkmcnt(0)
	v_cndmask_b32_e64 v21, 0, v21, s[16:17]
	v_add_u32_e32 v20, v21, v20
	v_sub_u32_e32 v19, v20, v19
	v_cmp_lt_i32_e32 vcc, s85, v20
	v_cmp_gt_i32_e64 s[26:27], s84, v19
	s_and_b64 vcc, vcc, s[26:27]
	s_and_b64 s[26:27], vcc, exec
	s_cbranch_vccz .LBB0_2594
	v_add_u32_e32 v4, v19, v18
	v_add_u32_e32 v17, v4, v17
	v_cmp_lt_i32_e32 vcc, s85, v17
	v_add_u32_e32 v16, v17, v16
	v_cmp_lt_i32_e64 s[28:29], s85, v4
	v_cndmask_b32_e32 v17, 0, v125, vcc
	v_cmp_lt_i32_e64 s[30:31], s85, v16
	v_cndmask_b32_e64 v4, v17, v124, s[28:29]
	v_add_u32_e32 v15, v16, v15
	v_cndmask_b32_e64 v16, v4, v126, s[30:31]
	s_or_b64 vcc, s[28:29], vcc
	v_cndmask_b32_e32 v4, v16, v4, vcc
	v_cmp_lt_i32_e64 s[28:29], s85, v15
	v_add_u32_e32 v14, v15, v14
	s_or_b64 vcc, vcc, s[30:31]
	v_cndmask_b32_e64 v15, v4, v127, s[28:29]
	v_cndmask_b32_e32 v4, v15, v4, vcc
	v_cmp_lt_i32_e64 s[30:31], s85, v14
	v_add_u32_e32 v13, v14, v13
	s_or_b64 vcc, vcc, s[28:29]
	v_cndmask_b32_e64 v14, v4, v128, s[30:31]
	v_cndmask_b32_e32 v4, v14, v4, vcc
	v_cmp_lt_i32_e64 s[28:29], s85, v13
	v_add_u32_e32 v12, v13, v12
	s_or_b64 vcc, vcc, s[30:31]
	v_cndmask_b32_e64 v13, v4, v129, s[28:29]
	v_cndmask_b32_e32 v4, v13, v4, vcc
	v_cmp_lt_i32_e64 s[30:31], s85, v12
	v_add_u32_e32 v11, v12, v11
	s_or_b64 vcc, vcc, s[28:29]
	v_cndmask_b32_e64 v12, v4, v130, s[30:31]
	v_cndmask_b32_e32 v4, v12, v4, vcc
	v_cmp_lt_i32_e64 s[28:29], s85, v11
	v_add_u32_e32 v10, v11, v10
	s_or_b64 vcc, vcc, s[30:31]
	v_cndmask_b32_e64 v11, v4, v131, s[28:29]
	v_cndmask_b32_e32 v4, v11, v4, vcc
	v_cmp_lt_i32_e64 s[30:31], s85, v10
	v_add_u32_e32 v9, v10, v9
	s_or_b64 vcc, vcc, s[28:29]
	v_cndmask_b32_e64 v10, v4, v132, s[30:31]
	v_cndmask_b32_e32 v4, v10, v4, vcc
	v_cmp_lt_i32_e64 s[28:29], s85, v9
	v_add_u32_e32 v8, v9, v8
	s_or_b64 vcc, vcc, s[30:31]
	v_cndmask_b32_e64 v9, v4, v133, s[28:29]
	v_cndmask_b32_e32 v4, v9, v4, vcc
	v_cmp_lt_i32_e64 s[30:31], s85, v8
	v_add_u32_e32 v7, v8, v7
	s_or_b64 vcc, vcc, s[28:29]
	v_cndmask_b32_e64 v8, v4, v134, s[30:31]
	v_cndmask_b32_e32 v4, v8, v4, vcc
	v_cmp_lt_i32_e64 s[28:29], s85, v7
	v_add_u32_e32 v3, v7, v3
	s_or_b64 vcc, vcc, s[30:31]
	v_cndmask_b32_e64 v7, v4, v135, s[28:29]
	v_cndmask_b32_e32 v4, v7, v4, vcc
	v_cmp_lt_i32_e64 s[30:31], s85, v3
	v_add_u32_e32 v6, v3, v6
	s_or_b64 vcc, vcc, s[28:29]
	v_cndmask_b32_e64 v3, v4, v136, s[30:31]
	v_add_u32_sdwa v18, v6, v2 dst_sel:DWORD dst_unused:UNUSED_PAD src0_sel:DWORD src1_sel:WORD_1
	v_cndmask_b32_e32 v3, v3, v4, vcc
	v_cmp_lt_i32_e64 s[28:29], s85, v6
	s_or_b64 vcc, vcc, s[30:31]
	v_add_u32_sdwa v2, v18, v2 dst_sel:DWORD dst_unused:UNUSED_PAD src0_sel:DWORD src1_sel:WORD_0
	v_cndmask_b32_e64 v4, v3, v137, s[28:29]
	v_cndmask_b32_e32 v4, v4, v3, vcc
	v_cmp_gt_i32_e64 s[30:31], s84, v2
	s_ff1_i32_b64 s0, s[26:27]
	s_nop 0
	v_cndmask_b32_e64 v2, v120, v4, s[30:31]
	v_cmp_lt_i32_e64 s[30:31], s85, v18
	s_nop 1
	v_cndmask_b32_e64 v2, v2, v138, s[30:31]
	v_cndmask_b32_e64 v2, v2, v137, s[28:29]
	v_cndmask_b32_e32 v2, v2, v3, vcc
	v_and_or_b32 v3, v160, 64, s0
	v_lshlrev_b32_e32 v3, 2, v3
	ds_bpermute_b32 v4, v3, v2

; DI void hist_select(const unsigned* hrow, int need, int lane, int& bsel, int& above, bool& hit) {
;     const u32x4 w0 = *(const u32x4*)(hrow + 8 * lane), w1 = *(const u32x4*)(hrow + 8 * lane + 4);
;     unsigned wv[8] = {w0.x, w0.y, w0.z, w0.w, w1.x, w1.y, w1.z, w1.w};
;     int cnt[16]; int tot = 0;
; #pragma unroll
;     for (int j = 0; j < 8; ++j) { cnt[2 * j] = (int)(wv[j] & 0xffffu); cnt[2 * j + 1] = (int)(wv[j] >> 16); tot += cnt[2 * j] + cnt[2 * j + 1]; }
;     int inc = tot;
; #pragma unroll
;     for (int d = 1; d < 64; d <<= 1) { const int o = __shfl_down(inc, d); if (lane + d < 64) inc += o; }
;     const int exc = inc - tot;
;     const bool pred = (inc >= need) && (exc < need);
;     const u64 bal = __ballot(pred);
;     int mybin = 0, myabove = exc; bool found = false; int run = exc;
; #pragma unroll
;     for (int j = 15; j >= 0; --j) { if (!found && run + cnt[j] >= need) { found = true; mybin = 16 * lane + j; myabove = run; } run += cnt[j]; }
;     hit = (bal != 0);
;     if (bal == 0) {
;         const int total = __shfl(inc, 0), c0 = __shfl(cnt[0], 0);
;         bsel = 0; above = total - c0;
;     } else {
;         const int L = __ffsll((long long)bal) - 1;
;         bsel = __shfl(mybin, L); above = __shfl(myabove, L);
;     }
.LBB0_2599:
	s_or_b64 exec, exec, s[26:27]
	ds_read_b128 v[2:5], v141
	ds_read_b128 v[22:25], v141 offset:16
	s_waitcnt lgkmcnt(1)
	v_add_u32_sdwa v14, v2, v2 dst_sel:DWORD dst_unused:UNUSED_PAD src0_sel:WORD_1 src1_sel:WORD_0
	v_and_b32_e32 v12, 0xffff, v3
	v_lshrrev_b32_e32 v3, 16, v3
	v_and_b32_e32 v13, 0xffff, v4
	v_add3_u32 v15, v14, v3, v12
	v_lshrrev_b32_e32 v14, 16, v4
	v_add3_u32 v4, v15, v14, v13
	v_and_b32_e32 v15, 0xffff, v5
	v_lshrrev_b32_e32 v16, 16, v5
	v_add3_u32 v4, v4, v16, v15
	s_waitcnt lgkmcnt(0)
	v_and_b32_e32 v17, 0xffff, v22
	v_lshrrev_b32_e32 v18, 16, v22
	v_add3_u32 v4, v4, v18, v17
	v_and_b32_e32 v19, 0xffff, v23
	v_lshrrev_b32_e32 v20, 16, v23
	v_add3_u32 v4, v4, v20, v19
	v_and_b32_e32 v21, 0xffff, v24
	v_lshrrev_b32_e32 v22, 16, v24
	v_add3_u32 v4, v4, v22, v21
	v_and_b32_e32 v23, 0xffff, v25
	v_lshrrev_b32_e32 v24, 16, v25
	v_add3_u32 v25, v4, v24, v23
	ds_bpermute_b32 v4, v1, v25
	s_waitcnt lgkmcnt(0)
	v_cndmask_b32_e64 v4, v4, 0, s[6:7]
	v_add_u32_e32 v4, v25, v4
	ds_bpermute_b32 v5, v104, v4
	s_waitcnt lgkmcnt(0)
	v_cndmask_b32_e64 v5, 0, v5, s[8:9]
	v_add_u32_e32 v4, v4, v5
	ds_bpermute_b32 v5, v105, v4
	s_waitcnt lgkmcnt(0)
	v_cndmask_b32_e64 v5, 0, v5, s[10:11]
	v_add_u32_e32 v4, v4, v5
	ds_bpermute_b32 v5, v106, v4
	s_waitcnt lgkmcnt(0)
	v_cndmask_b32_e64 v5, 0, v5, s[12:13]
	v_add_u32_e32 v4, v4, v5
	ds_bpermute_b32 v5, v108, v4
	s_waitcnt lgkmcnt(0)
	v_cndmask_b32_e64 v5, 0, v5, s[14:15]
	v_add_u32_e32 v26, v4, v5
	ds_bpermute_b32 v27, v83, v26
	v_mov_b32_e32 v4, 0
	v_mov_b32_e32 v5, 0
	s_waitcnt lgkmcnt(0)
	v_cndmask_b32_e64 v27, 0, v27, s[16:17]
	v_add_u32_e32 v27, v26, v27
	v_sub_u32_e32 v26, v27, v25
	v_cmp_lt_i32_e32 vcc, 31, v27
	v_cmp_gt_i32_e64 s[26:27], 32, v26
	s_and_b64 vcc, vcc, s[26:27]
	s_and_b64 s[26:27], vcc, exec
	s_cbranch_vccz .LBB0_2601
	v_add_u32_e32 v5, v26, v24
	v_add_u32_e32 v26, v5, v23
	v_cmp_lt_i32_e32 vcc, 31, v26
	v_add_u32_e32 v27, v26, v22
	v_cmp_lt_i32_e64 s[28:29], 31, v5
	v_cndmask_b32_e32 v26, 0, v125, vcc
	v_cmp_lt_i32_e64 s[30:31], 31, v27
	v_cndmask_b32_e64 v5, v26, v124, s[28:29]
	v_add_u32_e32 v28, v27, v21
	v_cndmask_b32_e64 v26, v5, v126, s[30:31]
	s_or_b64 vcc, s[28:29], vcc
	v_cndmask_b32_e32 v5, v26, v5, vcc
	v_cmp_lt_i32_e64 s[28:29], 31, v28
	v_add_u32_e32 v29, v28, v20
	s_or_b64 vcc, vcc, s[30:31]
	v_cndmask_b32_e64 v26, v5, v127, s[28:29]
	v_cndmask_b32_e32 v5, v26, v5, vcc
	v_cmp_lt_i32_e64 s[30:31], 31, v29
	v_add_u32_e32 v30, v29, v19
	s_or_b64 vcc, vcc, s[28:29]
	v_cndmask_b32_e64 v26, v5, v128, s[30:31]
	v_cndmask_b32_e32 v5, v26, v5, vcc
	v_cmp_lt_i32_e64 s[28:29], 31, v30
	v_add_u32_e32 v31, v30, v18
	s_or_b64 vcc, vcc, s[30:31]
	v_cndmask_b32_e64 v26, v5, v129, s[28:29]
	v_cndmask_b32_e32 v5, v26, v5, vcc
	v_cmp_lt_i32_e64 s[30:31], 31, v31
	v_add_u32_e32 v32, v31, v17
	s_or_b64 vcc, vcc, s[28:29]
	v_cndmask_b32_e64 v26, v5, v130, s[30:31]
	v_cndmask_b32_e32 v5, v26, v5, vcc
	v_cmp_lt_i32_e64 s[28:29], 31, v32
	v_add_u32_e32 v33, v32, v16
	s_or_b64 vcc, vcc, s[30:31]
	v_cndmask_b32_e64 v26, v5, v131, s[28:29]
	v_cndmask_b32_e32 v5, v26, v5, vcc
	v_cmp_lt_i32_e64 s[30:31], 31, v33
	s_waitcnt vmcnt(3)
	v_add_u32_e32 v66, v33, v15
	s_or_b64 vcc, vcc, s[28:29]
	v_cndmask_b32_e64 v26, v5, v132, s[30:31]
	v_cndmask_b32_e32 v5, v26, v5, vcc
	v_cmp_lt_i32_e64 s[28:29], 31, v66
	v_add_u32_e32 v67, v66, v14
	s_or_b64 vcc, vcc, s[30:31]
	v_cndmask_b32_e64 v26, v5, v133, s[28:29]
	v_cndmask_b32_e32 v5, v26, v5, vcc
	v_cmp_lt_i32_e64 s[30:31], 31, v67
	v_add_u32_e32 v68, v67, v13
	s_or_b64 vcc, vcc, s[28:29]
	v_cndmask_b32_e64 v26, v5, v134, s[30:31]
	v_cndmask_b32_e32 v5, v26, v5, vcc
	v_cmp_lt_i32_e64 s[28:29], 31, v68
	v_add_u32_e32 v69, v68, v3
	s_or_b64 vcc, vcc, s[30:31]
	v_cndmask_b32_e64 v26, v5, v135, s[28:29]
	v_cndmask_b32_e32 v5, v26, v5, vcc
	v_cmp_lt_i32_e64 s[30:31], 31, v69
	s_waitcnt vmcnt(2)
	v_add_u32_e32 v70, v69, v12
	s_or_b64 vcc, vcc, s[28:29]
	v_cndmask_b32_e64 v26, v5, v136, s[30:31]
	v_add_u32_sdwa v71, v70, v2 dst_sel:DWORD dst_unused:UNUSED_PAD src0_sel:DWORD src1_sel:WORD_1
	v_cndmask_b32_e32 v5, v26, v5, vcc
	v_cmp_lt_i32_e64 s[28:29], 31, v70
	s_or_b64 vcc, vcc, s[30:31]
	v_add_u32_sdwa v27, v71, v2 dst_sel:DWORD dst_unused:UNUSED_PAD src0_sel:DWORD src1_sel:WORD_0
	v_cndmask_b32_e64 v26, v5, v137, s[28:29]
	v_cndmask_b32_e32 v26, v26, v5, vcc
	v_cmp_gt_i32_e64 s[30:31], 32, v27
	s_ff1_i32_b64 s0, s[26:27]
	s_nop 0
	v_cndmask_b32_e64 v26, v120, v26, s[30:31]
	v_cmp_lt_i32_e64 s[30:31], 31, v71
	s_nop 1
	v_cndmask_b32_e64 v26, v26, v138, s[30:31]
	v_cndmask_b32_e64 v26, v26, v137, s[28:29]
	v_cndmask_b32_e32 v5, v26, v5, vcc
	v_and_or_b32 v26, v160, 64, s0
	v_lshlrev_b32_e32 v26, 2, v26
	ds_bpermute_b32 v5, v26, v5
; DI void hist_select(const unsigned* hrow, int need, int lane, int& bsel, int& above, bool& hit) {
;     const u32x4 w0 = *(const u32x4*)(hrow + 8 * lane), w1 = *(const u32x4*)(hrow + 8 * lane + 4);
;     unsigned wv[8] = {w0.x, w0.y, w0.z, w0.w, w1.x, w1.y, w1.z, w1.w};
;     int cnt[16]; int tot = 0;
; #pragma unroll
;     for (int j = 0; j < 8; ++j) { cnt[2 * j] = (int)(wv[j] & 0xffffu); cnt[2 * j + 1] = (int)(wv[j] >> 16); tot += cnt[2 * j] + cnt[2 * j + 1]; }
;     int inc = tot;
; #pragma unroll
;     for (int d = 1; d < 64; d <<= 1) { const int o = __shfl_down(inc, d); if (lane + d < 64) inc += o; }
;     const int exc = inc - tot;
;     const bool pred = (inc >= need) && (exc < need);
;     const u64 bal = __ballot(pred);
;     int mybin = 0, myabove = exc; bool found = false; int run = exc;
; #pragma unroll
;     for (int j = 15; j >= 0; --j) { if (!found && run + cnt[j] >= need) { found = true; mybin = 16 * lane + j; myabove = run; } run += cnt[j]; }
;     hit = (bal != 0);
;     if (bal == 0) {
;         const int total = __shfl(inc, 0), c0 = __shfl(cnt[0], 0);
;         bsel = 0; above = total - c0;
;     } else {
;         const int L = __ffsll((long long)bal) - 1;
;         bsel = __shfl(mybin, L); above = __shfl(myabove, L);
;     }
.LBB0_2601:
	ds_bpermute_b32 v26, v1, v25
	s_waitcnt lgkmcnt(0)
	v_cndmask_b32_e64 v26, v26, 0, s[6:7]
	v_add_u32_e32 v26, v26, v25
	ds_bpermute_b32 v27, v104, v26
	s_waitcnt lgkmcnt(0)
	v_cndmask_b32_e64 v27, 0, v27, s[8:9]
	v_add_u32_e32 v26, v27, v26
	ds_bpermute_b32 v27, v105, v26
	s_waitcnt lgkmcnt(0)
	v_cndmask_b32_e64 v27, 0, v27, s[10:11]
	v_add_u32_e32 v26, v27, v26
	ds_bpermute_b32 v27, v106, v26
	s_waitcnt lgkmcnt(0)
	v_cndmask_b32_e64 v27, 0, v27, s[12:13]
	v_add_u32_e32 v26, v27, v26
	ds_bpermute_b32 v27, v108, v26
	s_waitcnt lgkmcnt(0)
	v_cndmask_b32_e64 v27, 0, v27, s[14:15]
	v_add_u32_e32 v26, v27, v26
	ds_bpermute_b32 v27, v83, v26
	s_waitcnt lgkmcnt(0)
	v_cndmask_b32_e64 v27, 0, v27, s[16:17]
	v_add_u32_e32 v26, v27, v26
	v_sub_u32_e32 v25, v26, v25
	v_cmp_lt_i32_e32 vcc, s85, v26
	v_cmp_gt_i32_e64 s[26:27], s84, v25
	s_and_b64 vcc, vcc, s[26:27]
	s_and_b64 s[26:27], vcc, exec
	s_cbranch_vccz .LBB0_2603
	v_add_u32_e32 v4, v25, v24
	v_add_u32_e32 v23, v4, v23
	v_cmp_lt_i32_e32 vcc, s85, v23
	v_add_u32_e32 v22, v23, v22
	v_cmp_lt_i32_e64 s[28:29], s85, v4
	v_cndmask_b32_e32 v23, 0, v125, vcc
	v_cmp_lt_i32_e64 s[30:31], s85, v22
	v_cndmask_b32_e64 v4, v23, v124, s[28:29]
	v_add_u32_e32 v21, v22, v21
	v_cndmask_b32_e64 v22, v4, v126, s[30:31]
	s_or_b64 vcc, s[28:29], vcc
	v_cndmask_b32_e32 v4, v22, v4, vcc
	v_cmp_lt_i32_e64 s[28:29], s85, v21
	v_add_u32_e32 v20, v21, v20
	s_or_b64 vcc, vcc, s[30:31]
	v_cndmask_b32_e64 v21, v4, v127, s[28:29]
	v_cndmask_b32_e32 v4, v21, v4, vcc
	v_cmp_lt_i32_e64 s[30:31], s85, v20
	v_add_u32_e32 v19, v20, v19
	s_or_b64 vcc, vcc, s[28:29]
	v_cndmask_b32_e64 v20, v4, v128, s[30:31]
	v_cndmask_b32_e32 v4, v20, v4, vcc
	v_cmp_lt_i32_e64 s[28:29], s85, v19
	v_add_u32_e32 v18, v19, v18
	s_or_b64 vcc, vcc, s[30:31]
	v_cndmask_b32_e64 v19, v4, v129, s[28:29]
	v_cndmask_b32_e32 v4, v19, v4, vcc
	v_cmp_lt_i32_e64 s[30:31], s85, v18
	v_add_u32_e32 v17, v18, v17
	s_or_b64 vcc, vcc, s[28:29]
	v_cndmask_b32_e64 v18, v4, v130, s[30:31]
	v_cndmask_b32_e32 v4, v18, v4, vcc
	v_cmp_lt_i32_e64 s[28:29], s85, v17
	v_add_u32_e32 v16, v17, v16
	s_or_b64 vcc, vcc, s[30:31]
	v_cndmask_b32_e64 v17, v4, v131, s[28:29]
	v_cndmask_b32_e32 v4, v17, v4, vcc
	v_cmp_lt_i32_e64 s[30:31], s85, v16
	v_add_u32_e32 v15, v16, v15
	s_or_b64 vcc, vcc, s[28:29]
	v_cndmask_b32_e64 v16, v4, v132, s[30:31]
	v_cndmask_b32_e32 v4, v16, v4, vcc
	v_cmp_lt_i32_e64 s[28:29], s85, v15
	v_add_u32_e32 v14, v15, v14
	s_or_b64 vcc, vcc, s[30:31]
	v_cndmask_b32_e64 v15, v4, v133, s[28:29]
	v_cndmask_b32_e32 v4, v15, v4, vcc
	v_cmp_lt_i32_e64 s[30:31], s85, v14
	v_add_u32_e32 v13, v14, v13
	s_or_b64 vcc, vcc, s[28:29]
	v_cndmask_b32_e64 v14, v4, v134, s[30:31]
	v_cndmask_b32_e32 v4, v14, v4, vcc
	v_cmp_lt_i32_e64 s[28:29], s85, v13
	v_add_u32_e32 v3, v13, v3
	s_or_b64 vcc, vcc, s[30:31]
	v_cndmask_b32_e64 v13, v4, v135, s[28:29]
	v_cndmask_b32_e32 v4, v13, v4, vcc
	v_cmp_lt_i32_e64 s[30:31], s85, v3
	v_add_u32_e32 v12, v3, v12
	s_or_b64 vcc, vcc, s[28:29]
	v_cndmask_b32_e64 v3, v4, v136, s[30:31]
	v_add_u32_sdwa v24, v12, v2 dst_sel:DWORD dst_unused:UNUSED_PAD src0_sel:DWORD src1_sel:WORD_1
	v_cndmask_b32_e32 v3, v3, v4, vcc
	v_cmp_lt_i32_e64 s[28:29], s85, v12
	s_or_b64 vcc, vcc, s[30:31]
	v_add_u32_sdwa v2, v24, v2 dst_sel:DWORD dst_unused:UNUSED_PAD src0_sel:DWORD src1_sel:WORD_0
	v_cndmask_b32_e64 v4, v3, v137, s[28:29]
	v_cndmask_b32_e32 v4, v4, v3, vcc
	v_cmp_gt_i32_e64 s[30:31], s84, v2
	s_ff1_i32_b64 s0, s[26:27]
	s_nop 0
	v_cndmask_b32_e64 v2, v120, v4, s[30:31]
	v_cmp_lt_i32_e64 s[30:31], s85, v24
	s_nop 1
	v_cndmask_b32_e64 v2, v2, v138, s[30:31]
	v_cndmask_b32_e64 v2, v2, v137, s[28:29]
	v_cndmask_b32_e32 v2, v2, v3, vcc
	v_and_or_b32 v3, v160, 64, s0
	v_lshlrev_b32_e32 v3, 2, v3
	ds_bpermute_b32 v4, v3, v2

; DI void hist_select(const unsigned* hrow, int need, int lane, int& bsel, int& above, bool& hit) {
;     const u32x4 w0 = *(const u32x4*)(hrow + 8 * lane), w1 = *(const u32x4*)(hrow + 8 * lane + 4);
;     unsigned wv[8] = {w0.x, w0.y, w0.z, w0.w, w1.x, w1.y, w1.z, w1.w};
;     int cnt[16]; int tot = 0;
; #pragma unroll
;     for (int j = 0; j < 8; ++j) { cnt[2 * j] = (int)(wv[j] & 0xffffu); cnt[2 * j + 1] = (int)(wv[j] >> 16); tot += cnt[2 * j] + cnt[2 * j + 1]; }
;     int inc = tot;
; #pragma unroll
;     for (int d = 1; d < 64; d <<= 1) { const int o = __shfl_down(inc, d); if (lane + d < 64) inc += o; }
;     const int exc = inc - tot;
;     const bool pred = (inc >= need) && (exc < need);
;     const u64 bal = __ballot(pred);
;     int mybin = 0, myabove = exc; bool found = false; int run = exc;
; #pragma unroll
;     for (int j = 15; j >= 0; --j) { if (!found && run + cnt[j] >= need) { found = true; mybin = 16 * lane + j; myabove = run; } run += cnt[j]; }
;     hit = (bal != 0);
;     if (bal == 0) {
;         const int total = __shfl(inc, 0), c0 = __shfl(cnt[0], 0);
;         bsel = 0; above = total - c0;
;     } else {
;         const int L = __ffsll((long long)bal) - 1;
;         bsel = __shfl(mybin, L); above = __shfl(myabove, L);
;     }
.LBB0_2608:
	s_or_b64 exec, exec, s[26:27]
	ds_read_b128 v[2:5], v144
	ds_read_b128 v[22:25], v144 offset:16
	s_waitcnt lgkmcnt(1)
	v_add_u32_sdwa v14, v2, v2 dst_sel:DWORD dst_unused:UNUSED_PAD src0_sel:WORD_1 src1_sel:WORD_0
	v_and_b32_e32 v12, 0xffff, v3
	v_lshrrev_b32_e32 v3, 16, v3
	v_and_b32_e32 v13, 0xffff, v4
	v_add3_u32 v15, v14, v3, v12
	v_lshrrev_b32_e32 v14, 16, v4
	v_add3_u32 v4, v15, v14, v13
	v_and_b32_e32 v15, 0xffff, v5
	v_lshrrev_b32_e32 v16, 16, v5
	v_add3_u32 v4, v4, v16, v15
	s_waitcnt lgkmcnt(0)
	v_and_b32_e32 v17, 0xffff, v22
	v_lshrrev_b32_e32 v18, 16, v22
	v_add3_u32 v4, v4, v18, v17
	v_and_b32_e32 v19, 0xffff, v23
	v_lshrrev_b32_e32 v20, 16, v23
	v_add3_u32 v4, v4, v20, v19
	v_and_b32_e32 v21, 0xffff, v24
	v_lshrrev_b32_e32 v22, 16, v24
	v_add3_u32 v4, v4, v22, v21
	v_and_b32_e32 v23, 0xffff, v25
	v_lshrrev_b32_e32 v24, 16, v25
	v_add3_u32 v25, v4, v24, v23
	ds_bpermute_b32 v4, v1, v25
	s_waitcnt lgkmcnt(0)
	v_cndmask_b32_e64 v4, v4, 0, s[6:7]
	v_add_u32_e32 v4, v25, v4
	ds_bpermute_b32 v5, v104, v4
	s_waitcnt lgkmcnt(0)
	v_cndmask_b32_e64 v5, 0, v5, s[8:9]
	v_add_u32_e32 v4, v4, v5
	ds_bpermute_b32 v5, v105, v4
	s_waitcnt lgkmcnt(0)
	v_cndmask_b32_e64 v5, 0, v5, s[10:11]
	v_add_u32_e32 v4, v4, v5
	ds_bpermute_b32 v5, v106, v4
	s_waitcnt lgkmcnt(0)
	v_cndmask_b32_e64 v5, 0, v5, s[12:13]
	v_add_u32_e32 v4, v4, v5
	ds_bpermute_b32 v5, v108, v4
	s_waitcnt lgkmcnt(0)
	v_cndmask_b32_e64 v5, 0, v5, s[14:15]
	v_add_u32_e32 v26, v4, v5
	ds_bpermute_b32 v27, v83, v26
	v_mov_b32_e32 v4, 0
	v_mov_b32_e32 v5, 0
	s_waitcnt lgkmcnt(0)
	v_cndmask_b32_e64 v27, 0, v27, s[16:17]
	v_add_u32_e32 v27, v26, v27
	v_sub_u32_e32 v26, v27, v25
	v_cmp_lt_i32_e32 vcc, 31, v27
	v_cmp_gt_i32_e64 s[26:27], 32, v26
	s_and_b64 vcc, vcc, s[26:27]
	s_and_b64 s[26:27], vcc, exec
	s_cbranch_vccz .LBB0_2610
	v_add_u32_e32 v5, v26, v24
	v_add_u32_e32 v26, v5, v23
	v_cmp_lt_i32_e32 vcc, 31, v26
	v_add_u32_e32 v27, v26, v22
	v_cmp_lt_i32_e64 s[28:29], 31, v5
	v_cndmask_b32_e32 v26, 0, v125, vcc
	v_cmp_lt_i32_e64 s[30:31], 31, v27
	v_cndmask_b32_e64 v5, v26, v124, s[28:29]
	v_add_u32_e32 v28, v27, v21
	v_cndmask_b32_e64 v26, v5, v126, s[30:31]
	s_or_b64 vcc, s[28:29], vcc
	v_cndmask_b32_e32 v5, v26, v5, vcc
	v_cmp_lt_i32_e64 s[28:29], 31, v28
	v_add_u32_e32 v29, v28, v20
	s_or_b64 vcc, vcc, s[30:31]
	v_cndmask_b32_e64 v26, v5, v127, s[28:29]
	v_cndmask_b32_e32 v5, v26, v5, vcc
	v_cmp_lt_i32_e64 s[30:31], 31, v29
	v_add_u32_e32 v30, v29, v19
	s_or_b64 vcc, vcc, s[28:29]
	v_cndmask_b32_e64 v26, v5, v128, s[30:31]
	v_cndmask_b32_e32 v5, v26, v5, vcc
	v_cmp_lt_i32_e64 s[28:29], 31, v30
	v_add_u32_e32 v31, v30, v18
	s_or_b64 vcc, vcc, s[30:31]
	v_cndmask_b32_e64 v26, v5, v129, s[28:29]
	v_cndmask_b32_e32 v5, v26, v5, vcc
	v_cmp_lt_i32_e64 s[30:31], 31, v31
	v_add_u32_e32 v32, v31, v17
	s_or_b64 vcc, vcc, s[28:29]
	v_cndmask_b32_e64 v26, v5, v130, s[30:31]
	v_cndmask_b32_e32 v5, v26, v5, vcc
	v_cmp_lt_i32_e64 s[28:29], 31, v32
	v_add_u32_e32 v33, v32, v16
	s_or_b64 vcc, vcc, s[30:31]
	v_cndmask_b32_e64 v26, v5, v131, s[28:29]
	v_cndmask_b32_e32 v5, v26, v5, vcc
	v_cmp_lt_i32_e64 s[30:31], 31, v33
	s_waitcnt vmcnt(3)
	v_add_u32_e32 v66, v33, v15
	s_or_b64 vcc, vcc, s[28:29]
	v_cndmask_b32_e64 v26, v5, v132, s[30:31]
	v_cndmask_b32_e32 v5, v26, v5, vcc
	v_cmp_lt_i32_e64 s[28:29], 31, v66
	v_add_u32_e32 v67, v66, v14
	s_or_b64 vcc, vcc, s[30:31]
	v_cndmask_b32_e64 v26, v5, v133, s[28:29]
	v_cndmask_b32_e32 v5, v26, v5, vcc
	v_cmp_lt_i32_e64 s[30:31], 31, v67
	v_add_u32_e32 v68, v67, v13
	s_or_b64 vcc, vcc, s[28:29]
	v_cndmask_b32_e64 v26, v5, v134, s[30:31]
	v_cndmask_b32_e32 v5, v26, v5, vcc
	v_cmp_lt_i32_e64 s[28:29], 31, v68
	v_add_u32_e32 v69, v68, v3
	s_or_b64 vcc, vcc, s[30:31]
	v_cndmask_b32_e64 v26, v5, v135, s[28:29]
	v_cndmask_b32_e32 v5, v26, v5, vcc
	v_cmp_lt_i32_e64 s[30:31], 31, v69
	s_waitcnt vmcnt(2)
	v_add_u32_e32 v70, v69, v12
	s_or_b64 vcc, vcc, s[28:29]
	v_cndmask_b32_e64 v26, v5, v136, s[30:31]
	v_add_u32_sdwa v71, v70, v2 dst_sel:DWORD dst_unused:UNUSED_PAD src0_sel:DWORD src1_sel:WORD_1
	v_cndmask_b32_e32 v5, v26, v5, vcc
	v_cmp_lt_i32_e64 s[28:29], 31, v70
	s_or_b64 vcc, vcc, s[30:31]
	v_add_u32_sdwa v27, v71, v2 dst_sel:DWORD dst_unused:UNUSED_PAD src0_sel:DWORD src1_sel:WORD_0
	v_cndmask_b32_e64 v26, v5, v137, s[28:29]
	v_cndmask_b32_e32 v26, v26, v5, vcc
	v_cmp_gt_i32_e64 s[30:31], 32, v27
	s_ff1_i32_b64 s0, s[26:27]
	s_nop 0
	v_cndmask_b32_e64 v26, v120, v26, s[30:31]
	v_cmp_lt_i32_e64 s[30:31], 31, v71
	s_nop 1
	v_cndmask_b32_e64 v26, v26, v138, s[30:31]
	v_cndmask_b32_e64 v26, v26, v137, s[28:29]
	v_cndmask_b32_e32 v5, v26, v5, vcc
	v_and_or_b32 v26, v160, 64, s0
	v_lshlrev_b32_e32 v26, 2, v26
	ds_bpermute_b32 v5, v26, v5

; DI void hist_select(const unsigned* hrow, int need, int lane, int& bsel, int& above, bool& hit) {
;     const u32x4 w0 = *(const u32x4*)(hrow + 8 * lane), w1 = *(const u32x4*)(hrow + 8 * lane + 4);
;     unsigned wv[8] = {w0.x, w0.y, w0.z, w0.w, w1.x, w1.y, w1.z, w1.w};
;     int cnt[16]; int tot = 0;
; #pragma unroll
;     for (int j = 0; j < 8; ++j) { cnt[2 * j] = (int)(wv[j] & 0xffffu); cnt[2 * j + 1] = (int)(wv[j] >> 16); tot += cnt[2 * j] + cnt[2 * j + 1]; }
;     int inc = tot;
; #pragma unroll
;     for (int d = 1; d < 64; d <<= 1) { const int o = __shfl_down(inc, d); if (lane + d < 64) inc += o; }
;     const int exc = inc - tot;
;     const bool pred = (inc >= need) && (exc < need);
;     const u64 bal = __ballot(pred);
;     int mybin = 0, myabove = exc; bool found = false; int run = exc;
; #pragma unroll
;     for (int j = 15; j >= 0; --j) { if (!found && run + cnt[j] >= need) { found = true; mybin = 16 * lane + j; myabove = run; } run += cnt[j]; }
;     hit = (bal != 0);
;     if (bal == 0) {
;         const int total = __shfl(inc, 0), c0 = __shfl(cnt[0], 0);
;         bsel = 0; above = total - c0;
;     } else {
;         const int L = __ffsll((long long)bal) - 1;
;         bsel = __shfl(mybin, L); above = __shfl(myabove, L);
;     }
.LBB0_2617:
	s_or_b64 exec, exec, s[26:27]
	ds_read_b128 v[2:5], v147
	ds_read_b128 v[22:25], v147 offset:16
	s_waitcnt lgkmcnt(1)
	v_add_u32_sdwa v14, v2, v2 dst_sel:DWORD dst_unused:UNUSED_PAD src0_sel:WORD_1 src1_sel:WORD_0
	v_and_b32_e32 v12, 0xffff, v3
	v_lshrrev_b32_e32 v3, 16, v3
	v_and_b32_e32 v13, 0xffff, v4
	v_add3_u32 v15, v14, v3, v12
	v_lshrrev_b32_e32 v14, 16, v4
	v_add3_u32 v4, v15, v14, v13
	v_and_b32_e32 v15, 0xffff, v5
	v_lshrrev_b32_e32 v16, 16, v5
	v_add3_u32 v4, v4, v16, v15
	s_waitcnt lgkmcnt(0)
	v_and_b32_e32 v17, 0xffff, v22
	v_lshrrev_b32_e32 v18, 16, v22
	v_add3_u32 v4, v4, v18, v17
	v_and_b32_e32 v19, 0xffff, v23
	v_lshrrev_b32_e32 v20, 16, v23
	v_add3_u32 v4, v4, v20, v19
	v_and_b32_e32 v21, 0xffff, v24
	v_lshrrev_b32_e32 v22, 16, v24
	v_add3_u32 v4, v4, v22, v21
	v_and_b32_e32 v23, 0xffff, v25
	v_lshrrev_b32_e32 v24, 16, v25
	v_add3_u32 v25, v4, v24, v23
	ds_bpermute_b32 v4, v1, v25
	s_waitcnt lgkmcnt(0)
	v_cndmask_b32_e64 v4, v4, 0, s[6:7]
	v_add_u32_e32 v4, v25, v4
	ds_bpermute_b32 v5, v104, v4
	s_waitcnt lgkmcnt(0)
	v_cndmask_b32_e64 v5, 0, v5, s[8:9]
	v_add_u32_e32 v4, v4, v5
	ds_bpermute_b32 v5, v105, v4
	s_waitcnt lgkmcnt(0)
	v_cndmask_b32_e64 v5, 0, v5, s[10:11]
	v_add_u32_e32 v4, v4, v5
	ds_bpermute_b32 v5, v106, v4
	s_waitcnt lgkmcnt(0)
	v_cndmask_b32_e64 v5, 0, v5, s[12:13]
	v_add_u32_e32 v4, v4, v5
	ds_bpermute_b32 v5, v108, v4
	s_waitcnt lgkmcnt(0)
	v_cndmask_b32_e64 v5, 0, v5, s[14:15]
	v_add_u32_e32 v26, v4, v5
	ds_bpermute_b32 v27, v83, v26
	v_mov_b32_e32 v4, 0
	v_mov_b32_e32 v5, 0
	s_waitcnt lgkmcnt(0)
	v_cndmask_b32_e64 v27, 0, v27, s[16:17]
	v_add_u32_e32 v27, v26, v27
	v_sub_u32_e32 v26, v27, v25
	v_cmp_lt_i32_e32 vcc, 31, v27
	v_cmp_gt_i32_e64 s[26:27], 32, v26
	s_and_b64 vcc, vcc, s[26:27]
	s_and_b64 s[26:27], vcc, exec
	s_cbranch_vccz .LBB0_2619
	v_add_u32_e32 v5, v26, v24
	v_add_u32_e32 v26, v5, v23
	v_cmp_lt_i32_e32 vcc, 31, v26
	v_add_u32_e32 v27, v26, v22
	v_cmp_lt_i32_e64 s[28:29], 31, v5
	v_cndmask_b32_e32 v26, 0, v125, vcc
	v_cmp_lt_i32_e64 s[30:31], 31, v27
	v_cndmask_b32_e64 v5, v26, v124, s[28:29]
	v_add_u32_e32 v28, v27, v21
	v_cndmask_b32_e64 v26, v5, v126, s[30:31]
	s_or_b64 vcc, s[28:29], vcc
	v_cndmask_b32_e32 v5, v26, v5, vcc
	v_cmp_lt_i32_e64 s[28:29], 31, v28
	v_add_u32_e32 v29, v28, v20
	s_or_b64 vcc, vcc, s[30:31]
	v_cndmask_b32_e64 v26, v5, v127, s[28:29]
	v_cndmask_b32_e32 v5, v26, v5, vcc
	v_cmp_lt_i32_e64 s[30:31], 31, v29
	v_add_u32_e32 v30, v29, v19
	s_or_b64 vcc, vcc, s[28:29]
	v_cndmask_b32_e64 v26, v5, v128, s[30:31]
	v_cndmask_b32_e32 v5, v26, v5, vcc
	v_cmp_lt_i32_e64 s[28:29], 31, v30
	v_add_u32_e32 v31, v30, v18
	s_or_b64 vcc, vcc, s[30:31]
	v_cndmask_b32_e64 v26, v5, v129, s[28:29]
	v_cndmask_b32_e32 v5, v26, v5, vcc
	v_cmp_lt_i32_e64 s[30:31], 31, v31
	v_add_u32_e32 v32, v31, v17
	s_or_b64 vcc, vcc, s[28:29]
	v_cndmask_b32_e64 v26, v5, v130, s[30:31]
	v_cndmask_b32_e32 v5, v26, v5, vcc
	v_cmp_lt_i32_e64 s[28:29], 31, v32
	v_add_u32_e32 v33, v32, v16
	s_or_b64 vcc, vcc, s[30:31]
	v_cndmask_b32_e64 v26, v5, v131, s[28:29]
	v_cndmask_b32_e32 v5, v26, v5, vcc
	v_cmp_lt_i32_e64 s[30:31], 31, v33
	s_waitcnt vmcnt(3)
	v_add_u32_e32 v66, v33, v15
	s_or_b64 vcc, vcc, s[28:29]
	v_cndmask_b32_e64 v26, v5, v132, s[30:31]
	v_cndmask_b32_e32 v5, v26, v5, vcc
	v_cmp_lt_i32_e64 s[28:29], 31, v66
	v_add_u32_e32 v67, v66, v14
	s_or_b64 vcc, vcc, s[30:31]
	v_cndmask_b32_e64 v26, v5, v133, s[28:29]
	v_cndmask_b32_e32 v5, v26, v5, vcc
	v_cmp_lt_i32_e64 s[30:31], 31, v67
	v_add_u32_e32 v68, v67, v13
	s_or_b64 vcc, vcc, s[28:29]
	v_cndmask_b32_e64 v26, v5, v134, s[30:31]
	v_cndmask_b32_e32 v5, v26, v5, vcc
	v_cmp_lt_i32_e64 s[28:29], 31, v68
	v_add_u32_e32 v69, v68, v3
	s_or_b64 vcc, vcc, s[30:31]
	v_cndmask_b32_e64 v26, v5, v135, s[28:29]
	v_cndmask_b32_e32 v5, v26, v5, vcc
	v_cmp_lt_i32_e64 s[30:31], 31, v69
	s_waitcnt vmcnt(2)
	v_add_u32_e32 v70, v69, v12
	s_or_b64 vcc, vcc, s[28:29]
	v_cndmask_b32_e64 v26, v5, v136, s[30:31]
	v_add_u32_sdwa v71, v70, v2 dst_sel:DWORD dst_unused:UNUSED_PAD src0_sel:DWORD src1_sel:WORD_1
	v_cndmask_b32_e32 v5, v26, v5, vcc
	v_cmp_lt_i32_e64 s[28:29], 31, v70
	s_or_b64 vcc, vcc, s[30:31]
	v_add_u32_sdwa v27, v71, v2 dst_sel:DWORD dst_unused:UNUSED_PAD src0_sel:DWORD src1_sel:WORD_0
	v_cndmask_b32_e64 v26, v5, v137, s[28:29]
	v_cndmask_b32_e32 v26, v26, v5, vcc
	v_cmp_gt_i32_e64 s[30:31], 32, v27
	s_ff1_i32_b64 s0, s[26:27]
	s_nop 0
	v_cndmask_b32_e64 v26, v120, v26, s[30:31]
	v_cmp_lt_i32_e64 s[30:31], 31, v71
	s_nop 1
	v_cndmask_b32_e64 v26, v26, v138, s[30:31]
	v_cndmask_b32_e64 v26, v26, v137, s[28:29]
	v_cndmask_b32_e32 v5, v26, v5, vcc
	v_and_or_b32 v26, v160, 64, s0
	v_lshlrev_b32_e32 v26, 2, v26
	ds_bpermute_b32 v5, v26, v5

; DI void hist_select(const unsigned* hrow, int need, int lane, int& bsel, int& above, bool& hit) {
;     ...
;     const bool pred = (inc >= need) && (exc < need);
;     const u64 bal = __ballot(pred);
;     int mybin = 0, myabove = exc; bool found = false; int run = exc;
; #pragma unroll
;     for (int j = 15; j >= 0; --j) { if (!found && run + cnt[j] >= need) { found = true; mybin = 16 * lane + j; myabove = run; } run += cnt[j]; }
;     hit = (bal != 0);
;     if (bal == 0) {
;         const int total = __shfl(inc, 0), c0 = __shfl(cnt[0], 0);
;         bsel = 0; above = total - c0;
;     } else {
;         const int L = __ffsll((long long)bal) - 1;
;         bsel = __shfl(mybin, L); above = __shfl(myabove, L);
;     }
.LBB0_2760:
	s_or_b64 exec, exec, s[28:29]
	v_cmp_ge_i32_e32 vcc, v4, v5
	v_cmp_lt_i32_e64 s[28:29], v7, v5
	s_and_b64 vcc, vcc, s[28:29]
	s_and_b64 s[28:29], vcc, exec
	s_cbranch_vccz .LBB0_3567
	v_add_u32_e32 v7, v2, v12
	v_cmp_lt_i32_e32 vcc, v7, v5
	s_ff1_i32_b64 s0, s[28:29]
	s_or_b64 vcc, s[30:31], vcc
	v_or_b32_e32 v7, s0, v6
	v_cndmask_b32_e32 v2, v2, v14, vcc
	v_cndmask_b32_e32 v5, v120, v15, vcc
	v_lshlrev_b32_e32 v7, 2, v7
	ds_bpermute_b32 v5, v7, v5
	ds_bpermute_b32 v2, v7, v2
	v_and_b32_e32 v7, 0x100, v109
	s_cbranch_execnz .LBB0_2763

; DI void hist_select(const unsigned* hrow, int need, int lane, int& bsel, int& above, bool& hit) {
;     ...
;     const bool pred = (inc >= need) && (exc < need);
;     const u64 bal = __ballot(pred);
;     int mybin = 0, myabove = exc; bool found = false; int run = exc;
; #pragma unroll
;     for (int j = 15; j >= 0; --j) { if (!found && run + cnt[j] >= need) { found = true; mybin = 16 * lane + j; myabove = run; } run += cnt[j]; }
;     hit = (bal != 0);
;     if (bal == 0) {
;         const int total = __shfl(inc, 0), c0 = __shfl(cnt[0], 0);
;         bsel = 0; above = total - c0;
;     } else {
;         const int L = __ffsll((long long)bal) - 1;
;         bsel = __shfl(mybin, L); above = __shfl(myabove, L);
;     }
.LBB0_2823:
	s_or_b64 exec, exec, s[28:29]
	v_cmp_ge_i32_e32 vcc, v4, v5
	v_cmp_lt_i32_e64 s[28:29], v11, v5
	s_and_b64 vcc, vcc, s[28:29]
	s_and_b64 s[28:29], vcc, exec
	s_cbranch_vccz .LBB0_3568
	v_add_u32_e32 v11, v2, v12
	v_cmp_lt_i32_e32 vcc, v11, v5
	s_ff1_i32_b64 s0, s[28:29]
	s_or_b64 vcc, s[30:31], vcc
	v_or_b32_e32 v11, s0, v6
	v_cndmask_b32_e32 v2, v2, v15, vcc
	v_cndmask_b32_e32 v5, v120, v14, vcc
	v_lshlrev_b32_e32 v11, 2, v11
	ds_bpermute_b32 v5, v11, v5
	ds_bpermute_b32 v2, v11, v2
	s_cbranch_execnz .LBB0_2826

; DI void hist_select(const unsigned* hrow, int need, int lane, int& bsel, int& above, bool& hit) {
;     ...
;     const bool pred = (inc >= need) && (exc < need);
;     const u64 bal = __ballot(pred);
;     int mybin = 0, myabove = exc; bool found = false; int run = exc;
; #pragma unroll
;     for (int j = 15; j >= 0; --j) { if (!found && run + cnt[j] >= need) { found = true; mybin = 16 * lane + j; myabove = run; } run += cnt[j]; }
;     hit = (bal != 0);
;     if (bal == 0) {
;         const int total = __shfl(inc, 0), c0 = __shfl(cnt[0], 0);
;         bsel = 0; above = total - c0;
;     } else {
;         const int L = __ffsll((long long)bal) - 1;
;         bsel = __shfl(mybin, L); above = __shfl(myabove, L);
;     }
.LBB0_2886:
	s_or_b64 exec, exec, s[28:29]
	v_cmp_ge_i32_e32 vcc, v4, v5
	v_cmp_lt_i32_e64 s[28:29], v10, v5
	s_and_b64 vcc, vcc, s[28:29]
	s_and_b64 s[28:29], vcc, exec
	s_cbranch_vccz .LBB0_3569
	v_add_u32_e32 v10, v2, v11
	v_cmp_lt_i32_e32 vcc, v10, v5
	s_ff1_i32_b64 s0, s[28:29]
	s_or_b64 vcc, s[30:31], vcc
	v_or_b32_e32 v10, s0, v6
	v_cndmask_b32_e32 v2, v2, v14, vcc
	v_cndmask_b32_e32 v5, v120, v13, vcc
	v_lshlrev_b32_e32 v10, 2, v10
	ds_bpermute_b32 v5, v10, v5
	ds_bpermute_b32 v2, v10, v2
	s_cbranch_execnz .LBB0_2889

; DI void hist_select(const unsigned* hrow, int need, int lane, int& bsel, int& above, bool& hit) {
;     ...
;     const bool pred = (inc >= need) && (exc < need);
;     const u64 bal = __ballot(pred);
;     int mybin = 0, myabove = exc; bool found = false; int run = exc;
; #pragma unroll
;     for (int j = 15; j >= 0; --j) { if (!found && run + cnt[j] >= need) { found = true; mybin = 16 * lane + j; myabove = run; } run += cnt[j]; }
;     hit = (bal != 0);
;     if (bal == 0) {
;         const int total = __shfl(inc, 0), c0 = __shfl(cnt[0], 0);
;         bsel = 0; above = total - c0;
;     } else {
;         const int L = __ffsll((long long)bal) - 1;
;         bsel = __shfl(mybin, L); above = __shfl(myabove, L);
;     }
.LBB0_2949:
	s_or_b64 exec, exec, s[28:29]
	v_cmp_ge_i32_e32 vcc, v3, v4
	v_cmp_lt_i32_e64 s[28:29], v5, v4
	s_and_b64 vcc, vcc, s[28:29]
	s_and_b64 s[28:29], vcc, exec
	s_cbranch_vccz .LBB0_3570
	v_add_u32_e32 v5, v2, v8
	v_cmp_lt_i32_e32 vcc, v5, v4
	s_ff1_i32_b64 s0, s[28:29]
	s_or_b64 vcc, s[30:31], vcc
	v_or_b32_e32 v5, s0, v6
	v_cndmask_b32_e32 v2, v2, v11, vcc
	v_cndmask_b32_e32 v4, v120, v9, vcc
	v_lshlrev_b32_e32 v5, 2, v5
	ds_bpermute_b32 v4, v5, v4
	ds_bpermute_b32 v2, v5, v2
	s_cbranch_execnz .LBB0_2952

; DI void hist_select(const unsigned* hrow, int need, int lane, int& bsel, int& above, bool& hit) {
;     ...
;     const bool pred = (inc >= need) && (exc < need);
;     const u64 bal = __ballot(pred);
;     int mybin = 0, myabove = exc; bool found = false; int run = exc;
; #pragma unroll
;     for (int j = 15; j >= 0; --j) { if (!found && run + cnt[j] >= need) { found = true; mybin = 16 * lane + j; myabove = run; } run += cnt[j]; }
;     hit = (bal != 0);
;     if (bal == 0) {
;         const int total = __shfl(inc, 0), c0 = __shfl(cnt[0], 0);
;         bsel = 0; above = total - c0;
;     } else {
;         const int L = __ffsll((long long)bal) - 1;
;         bsel = __shfl(mybin, L); above = __shfl(myabove, L);
;     }
.LBB0_3046:
	s_or_b64 exec, exec, s[26:27]
	v_cmp_lt_i32_e32 vcc, s89, v4
	v_cmp_gt_i32_e64 s[26:27], s83, v5
	s_and_b64 vcc, vcc, s[26:27]
	s_and_b64 s[26:27], vcc, exec
	s_cbranch_vccz .LBB0_3571
	v_add_u32_e32 v5, v2, v6
	v_cmp_gt_i32_e32 vcc, s83, v5
	s_ff1_i32_b64 s0, s[26:27]
	s_or_b64 vcc, s[30:31], vcc
	v_and_or_b32 v7, v160, 64, s0
	v_cndmask_b32_e32 v5, v2, v8, vcc
	v_cndmask_b32_e32 v2, v120, v10, vcc
	v_lshlrev_b32_e32 v7, 2, v7
	ds_bpermute_b32 v2, v7, v2
	ds_bpermute_b32 v5, v7, v5
	v_and_b32_e32 v100, 0x100, v3
	s_cbranch_execnz .LBB0_3049

; DI void hist_select(const unsigned* hrow, int need, int lane, int& bsel, int& above, bool& hit) {
;     ...
;     const bool pred = (inc >= need) && (exc < need);
;     const u64 bal = __ballot(pred);
;     int mybin = 0, myabove = exc; bool found = false; int run = exc;
; #pragma unroll
;     for (int j = 15; j >= 0; --j) { if (!found && run + cnt[j] >= need) { found = true; mybin = 16 * lane + j; myabove = run; } run += cnt[j]; }
;     hit = (bal != 0);
;     if (bal == 0) {
;         const int total = __shfl(inc, 0), c0 = __shfl(cnt[0], 0);
;         bsel = 0; above = total - c0;
;     } else {
;         const int L = __ffsll((long long)bal) - 1;
;         bsel = __shfl(mybin, L); above = __shfl(myabove, L);
;     }
.LBB0_3107:
	s_or_b64 exec, exec, s[26:27]
	v_cmp_lt_i32_e32 vcc, s89, v3
	v_cmp_gt_i32_e64 s[26:27], s83, v4
	s_and_b64 vcc, vcc, s[26:27]
	s_and_b64 s[26:27], vcc, exec
	s_cbranch_vccz .LBB0_3572
	v_add_u32_e32 v4, v2, v6
	v_cmp_gt_i32_e32 vcc, s83, v4
	s_or_b64 vcc, s[30:31], vcc
	s_ff1_i32_b64 s0, s[26:27]
	v_cndmask_b32_e32 v4, v2, v5, vcc
	v_and_or_b32 v5, v160, 64, s0
	v_cndmask_b32_e32 v2, v120, v8, vcc
	v_lshlrev_b32_e32 v5, 2, v5
	ds_bpermute_b32 v2, v5, v2
	ds_bpermute_b32 v4, v5, v4
	s_cbranch_execnz .LBB0_3110

; DI void hist_select(const unsigned* hrow, int need, int lane, int& bsel, int& above, bool& hit) {
;     ...
;     const bool pred = (inc >= need) && (exc < need);
;     const u64 bal = __ballot(pred);
;     int mybin = 0, myabove = exc; bool found = false; int run = exc;
; #pragma unroll
;     for (int j = 15; j >= 0; --j) { if (!found && run + cnt[j] >= need) { found = true; mybin = 16 * lane + j; myabove = run; } run += cnt[j]; }
;     hit = (bal != 0);
;     if (bal == 0) {
;         const int total = __shfl(inc, 0), c0 = __shfl(cnt[0], 0);
;         bsel = 0; above = total - c0;
;     } else {
;         const int L = __ffsll((long long)bal) - 1;
;         bsel = __shfl(mybin, L); above = __shfl(myabove, L);
;     }
.LBB0_3324:
	s_or_b64 exec, exec, s[26:27]
	v_cmp_ge_i32_e32 vcc, v4, v5
	v_cmp_lt_i32_e64 s[26:27], v8, v5
	s_and_b64 vcc, vcc, s[26:27]
	v_and_b32_e32 v6, 64, v160
	s_and_b64 s[26:27], vcc, exec
	s_cbranch_vccz .LBB0_3575
	v_add_u32_e32 v8, v2, v7
	v_cmp_lt_i32_e32 vcc, v8, v5
	s_ff1_i32_b64 s0, s[26:27]
	s_or_b64 vcc, s[28:29], vcc
	v_or_b32_e32 v8, s0, v6
	v_cndmask_b32_e32 v5, v2, v9, vcc
	v_cndmask_b32_e32 v2, v120, v10, vcc
	v_lshlrev_b32_e32 v8, 2, v8
	ds_bpermute_b32 v2, v8, v2
	ds_bpermute_b32 v5, v8, v5
	s_cbranch_execnz .LBB0_3327

; DI void hist_select(const unsigned* hrow, int need, int lane, int& bsel, int& above, bool& hit) {
;     ...
;     const bool pred = (inc >= need) && (exc < need);
;     const u64 bal = __ballot(pred);
;     int mybin = 0, myabove = exc; bool found = false; int run = exc;
; #pragma unroll
;     for (int j = 15; j >= 0; --j) { if (!found && run + cnt[j] >= need) { found = true; mybin = 16 * lane + j; myabove = run; } run += cnt[j]; }
;     hit = (bal != 0);
;     if (bal == 0) {
;         const int total = __shfl(inc, 0), c0 = __shfl(cnt[0], 0);
;         bsel = 0; above = total - c0;
;     } else {
;         const int L = __ffsll((long long)bal) - 1;
;         bsel = __shfl(mybin, L); above = __shfl(myabove, L);
;     }
.LBB0_3385:
	s_or_b64 exec, exec, s[26:27]
	v_cmp_ge_i32_e32 vcc, v4, v5
	v_cmp_lt_i32_e64 s[26:27], v8, v5
	s_and_b64 vcc, vcc, s[26:27]
	s_and_b64 s[26:27], vcc, exec
	s_cbranch_vccz .LBB0_3576
	v_add_u32_e32 v8, v2, v7
	v_cmp_lt_i32_e32 vcc, v8, v5
	s_ff1_i32_b64 s0, s[26:27]
	s_or_b64 vcc, s[28:29], vcc
	v_or_b32_e32 v8, s0, v6
	v_cndmask_b32_e32 v5, v2, v10, vcc
	v_cndmask_b32_e32 v2, v120, v11, vcc
	v_lshlrev_b32_e32 v8, 2, v8
	ds_bpermute_b32 v2, v8, v2
	ds_bpermute_b32 v5, v8, v5
	s_cbranch_execnz .LBB0_3388

; DI void hist_select(const unsigned* hrow, int need, int lane, int& bsel, int& above, bool& hit) {
;     ...
;     const bool pred = (inc >= need) && (exc < need);
;     const u64 bal = __ballot(pred);
;     int mybin = 0, myabove = exc; bool found = false; int run = exc;
; #pragma unroll
;     for (int j = 15; j >= 0; --j) { if (!found && run + cnt[j] >= need) { found = true; mybin = 16 * lane + j; myabove = run; } run += cnt[j]; }
;     hit = (bal != 0);
;     if (bal == 0) {
;         const int total = __shfl(inc, 0), c0 = __shfl(cnt[0], 0);
;         bsel = 0; above = total - c0;
;     } else {
;         const int L = __ffsll((long long)bal) - 1;
;         bsel = __shfl(mybin, L); above = __shfl(myabove, L);
;     }
.LBB0_3507:
	s_or_b64 exec, exec, s[26:27]
	v_cmp_ge_i32_e32 vcc, v3, v4
	v_cmp_lt_i32_e64 s[26:27], v5, v4
	s_and_b64 vcc, vcc, s[26:27]
	s_and_b64 s[26:27], vcc, exec
	s_cbranch_vccz .LBB0_3578
	v_add_u32_e32 v5, v2, v7
	v_cmp_lt_i32_e32 vcc, v5, v4
	s_ff1_i32_b64 s0, s[26:27]
	s_or_b64 vcc, s[28:29], vcc
	v_or_b32_e32 v5, s0, v6
	v_cndmask_b32_e32 v4, v2, v9, vcc
	v_cndmask_b32_e32 v2, v120, v10, vcc
	v_lshlrev_b32_e32 v5, 2, v5
	ds_bpermute_b32 v2, v5, v2
	ds_bpermute_b32 v4, v5, v4
	s_cbranch_execnz .LBB0_3510

;     ...
;             if (__ballot(shift != 0.f) != 0) {
;                 if (__ballot(up) != 0) {
;                     const float alpha = __builtin_amdgcn_exp2f(m - mn);
;                     l *= alpha;
; #pragma unroll
;                     for (int db = 0; db < DVB; ++db)
; #pragma unroll
;                         for (int i = 0; i < 16; ++i) o[db][i] *= alpha;
;                     m = mn;
;                 }
.Lil1_cont:
	s_and_b64 vcc, s[4:5], exec
	s_cbranch_vccz .LBB0_3632
	v_sub_f32_e32 v34, v183, v189
	v_exp_f32_e32 v114, v34
	s_nop 0
	v_mul_f32_e32 v209, v173, v114
	v_pk_mul_f32 v[48:49], v[112:113], v[114:115] op_sel_hi:[1,0]
	v_pk_mul_f32 v[46:47], v[110:111], v[114:115] op_sel_hi:[1,0]
	v_pk_mul_f32 v[44:45], v[108:109], v[114:115] op_sel_hi:[1,0]
	v_pk_mul_f32 v[42:43], v[106:107], v[114:115] op_sel_hi:[1,0]
	v_pk_mul_f32 v[40:41], v[104:105], v[114:115] op_sel_hi:[1,0]
	v_pk_mul_f32 v[38:39], v[102:103], v[114:115] op_sel_hi:[1,0]
	v_pk_mul_f32 v[36:37], v[100:101], v[114:115] op_sel_hi:[1,0]
	v_pk_mul_f32 v[34:35], v[98:99], v[114:115] op_sel_hi:[1,0]
	v_pk_mul_f32 v[128:129], v[96:97], v[114:115] op_sel_hi:[1,0]
	v_pk_mul_f32 v[126:127], v[94:95], v[114:115] op_sel_hi:[1,0]
	v_pk_mul_f32 v[124:125], v[92:93], v[114:115] op_sel_hi:[1,0]
	v_pk_mul_f32 v[122:123], v[90:91], v[114:115] op_sel_hi:[1,0]
	v_pk_mul_f32 v[120:121], v[88:89], v[114:115] op_sel_hi:[1,0]
	v_pk_mul_f32 v[118:119], v[86:87], v[114:115] op_sel_hi:[1,0]
	v_pk_mul_f32 v[116:117], v[84:85], v[114:115] op_sel_hi:[1,0]
	v_pk_mul_f32 v[114:115], v[82:83], v[114:115] op_sel_hi:[1,0]
	s_cbranch_execnz .LBB0_3616

;     ...
;             if (__ballot(shift != 0.f) != 0) {
;                 if (__ballot(up) != 0) {
;                     const float alpha = __builtin_amdgcn_exp2f(m - mn);
;                     l *= alpha;
; #pragma unroll
;                     for (int db = 0; db < DVB; ++db)
; #pragma unroll
;                         for (int i = 0; i < 16; ++i) o[db][i] *= alpha;
;                     m = mn;
;                 }
.Lil2_cont:
	s_and_b64 vcc, s[6:7], exec
	s_cbranch_vccz .LBB0_3633
	v_sub_f32_e32 v52, v183, v50
	v_exp_f32_e32 v52, v52
	s_nop 0
	v_mul_f32_e32 v173, v173, v52
	v_pk_mul_f32 v[112:113], v[112:113], v[52:53] op_sel_hi:[1,0]
	v_pk_mul_f32 v[110:111], v[110:111], v[52:53] op_sel_hi:[1,0]
	v_pk_mul_f32 v[108:109], v[108:109], v[52:53] op_sel_hi:[1,0]
	v_pk_mul_f32 v[106:107], v[106:107], v[52:53] op_sel_hi:[1,0]
	v_pk_mul_f32 v[104:105], v[104:105], v[52:53] op_sel_hi:[1,0]
	v_pk_mul_f32 v[102:103], v[102:103], v[52:53] op_sel_hi:[1,0]
	v_pk_mul_f32 v[100:101], v[100:101], v[52:53] op_sel_hi:[1,0]
	v_pk_mul_f32 v[98:99], v[98:99], v[52:53] op_sel_hi:[1,0]
	v_pk_mul_f32 v[96:97], v[96:97], v[52:53] op_sel_hi:[1,0]
	v_pk_mul_f32 v[94:95], v[94:95], v[52:53] op_sel_hi:[1,0]
	v_pk_mul_f32 v[92:93], v[92:93], v[52:53] op_sel_hi:[1,0]
	v_pk_mul_f32 v[90:91], v[90:91], v[52:53] op_sel_hi:[1,0]
	v_pk_mul_f32 v[88:89], v[88:89], v[52:53] op_sel_hi:[1,0]
	v_pk_mul_f32 v[86:87], v[86:87], v[52:53] op_sel_hi:[1,0]
	v_pk_mul_f32 v[84:85], v[84:85], v[52:53] op_sel_hi:[1,0]
	v_pk_mul_f32 v[82:83], v[82:83], v[52:53] op_sel_hi:[1,0]
	s_branch .LBB0_3634
